# hand-written LayerNorm keeps one row pair of loads ahead of the reductions instead of two
# baseline (speedup 1.0000x reference)
.LBB0_38:
	s_add_i32 s34, s60, -2
	s_mul_hi_i32 s35, s34, 0x2aaaaaab
	s_lshr_b32 s36, s35, 31
	s_ashr_i32 s35, s35, 1
	s_add_i32 s6, s35, s36
	s_mov_b32 s4, s6
	v_writelane_b32 v235, s4, 44
	s_mul_i32 s35, s6, 12
	s_sub_i32 s6, s34, s35
	v_writelane_b32 v235, s5, 45
	v_writelane_b32 v235, s60, 46
	s_lshl_b32 s34, s60, 6
	s_ashr_i32 s35, s34, 31
	s_lshl_b64 s[34:35], s[34:35], 2
	v_readlane_b32 s4, v236, 19
	s_add_u32 s8, s4, s34
	v_readlane_b32 s4, v236, 20
	v_writelane_b32 v235, s61, 47
	s_addc_u32 s9, s4, s35
	v_writelane_b32 v235, s8, 36
	s_mov_b64 s[34:35], -1
	s_mov_b64 s[40:41], 0
	v_writelane_b32 v235, s9, 37
	s_nop 0
	v_readlane_b32 s4, v235, 34
	v_readlane_b32 s5, v235, 35
	s_add_u32 s60, s4, 0xfae6000
	s_addc_u32 s61, s5, 0
	v_writelane_b32 v235, s6, 48
	s_mov_b64 s[4:5], 0
	v_writelane_b32 v235, s4, 49
	s_cmp_lt_i32 s6, 6
	s_nop 0
	v_writelane_b32 v235, s5, 50
	s_mov_b64 s[4:5], 0
	v_writelane_b32 v235, s4, 51
	s_nop 1
	v_writelane_b32 v235, s5, 52
	s_cbranch_scc1 .LBB0_134
	v_readlane_b32 s4, v235, 48
	s_cmp_gt_i32 s4, 8
	s_cbranch_scc0 .LBB0_85
	s_mov_b64 s[6:7], -1
	v_writelane_b32 v235, s6, 49
	s_mov_b64 s[44:45], 0
	s_cmp_gt_i32 s4, 9
	v_writelane_b32 v235, s7, 50
	s_mov_b64 s[6:7], 0
	s_cbranch_scc0 .LBB0_89
	v_readlane_b32 s2, v235, 48
	s_cmp_gt_i32 s2, 10
	s_mov_b64 s[6:7], -1
	s_cbranch_scc0 .LBB0_88
	v_readlane_b32 s2, v235, 48
	s_cmp_eq_u32 s2, 11
	s_cbranch_scc0 .LBB0_87
	v_mov_b32_e32 v33, v170
	v_mov_b32_e32 v0, v170
	v_readlane_b32 s4, v235, 17
	s_waitcnt lgkmcnt(0)
	v_ashrrev_i32_e32 v34, 6, v0
	s_mov_b64 s[88:89], s[74:75]
	v_add_u32_e32 v32, s4, v34
	s_movk_i32 s4, 0x3000
	v_cmp_gt_i32_e32 vcc, s4, v32
	s_and_saveexec_b64 s[46:47], vcc
	s_cbranch_execz .LBB0_86
	v_readlane_b32 s4, v235, 33
	s_cmp_lg_u32 s4, 0x200
	s_cbranch_scc1 .Llna_orig
	v_and_b32_e32 v232, 63, v170
	v_lshlrev_b32_e32 v233, 3, v232
	v_lshlrev_b32_e32 v232, 4, v232
	v_lshrrev_b32_e32 v231, 6, v170
	s_nop 0
	v_readfirstlane_b32 s6, v231
	v_readlane_b32 s7, v237, 0
	s_lshl_b32 s7, s7, 2
	s_add_u32 s6, s6, s7
	v_readlane_b32 s8, v235, 34
	v_readlane_b32 s9, v235, 35
	v_readlane_b32 s7, v235, 44
	s_mul_i32 s10, s7, 3
	s_add_u32 s10, s10, 2
	s_lshl_b32 s10, s10, 12
	v_readlane_b32 s4, v237, 25
	v_readlane_b32 s5, v237, 26
	s_add_u32 s4, s4, s10
	s_addc_u32 s5, s5, 0
	global_load_dwordx4 v[136:139], v232, s[4:5]
	global_load_dwordx4 v[140:143], v232, s[4:5] offset:1024
	global_load_dwordx4 v[144:147], v232, s[4:5] offset:2048
	global_load_dwordx4 v[148:151], v232, s[4:5] offset:3072
	v_readlane_b32 s4, v237, 27
	v_readlane_b32 s5, v237, 28
	s_add_u32 s4, s4, s10
	s_addc_u32 s5, s5, 0
	global_load_dwordx4 v[152:155], v232, s[4:5]
	global_load_dwordx4 v[156:159], v232, s[4:5] offset:1024
	global_load_dwordx4 v[160:163], v232, s[4:5] offset:2048
	global_load_dwordx4 v[164:167], v232, s[4:5] offset:3072
	s_cmp_lt_u32 s7, 3
	s_addc_u32 s11, s7, 0
	s_mul_i32 s11, s11, 0x1b000
	s_add_u32 s11, s11, 0xb0f8000
	s_add_u32 s10, s8, s11
	s_addc_u32 s11, s9, 0
	s_cmp_eq_u32 s7, 3
	s_cselect_b32 s57, 1, 0
	s_add_u32 s4, s10, 0x0
	s_addc_u32 s5, s11, 0
	global_load_dwordx4 v[64:67], v232, s[4:5]
	global_load_dwordx4 v[68:71], v232, s[4:5] offset:1024
	global_load_dwordx4 v[72:75], v232, s[4:5] offset:2048
	global_load_dwordx4 v[76:79], v232, s[4:5] offset:3072
	s_add_u32 s4, s4, 0x1000
	s_addc_u32 s5, s5, 0
	global_load_dwordx4 v[80:83], v232, s[4:5]
	global_load_dwordx4 v[84:87], v232, s[4:5] offset:1024
	global_load_dwordx4 v[88:91], v232, s[4:5] offset:2048
	global_load_dwordx4 v[92:95], v232, s[4:5] offset:3072
	s_lshl_b32 s4, s6, 12
	s_add_u32 s4, s4, 0xb166000
	s_add_u32 s4, s4, s8
	s_addc_u32 s5, s9, 0
	global_load_dwordx4 v[0:3], v232, s[4:5]
	global_load_dwordx4 v[4:7], v232, s[4:5] offset:1024
	global_load_dwordx4 v[8:11], v232, s[4:5] offset:2048
	global_load_dwordx4 v[12:15], v232, s[4:5] offset:3072
	s_lshl_b32 s4, s6, 12
	s_add_u32 s4, s4, 0xb966000
	s_add_u32 s4, s4, s8
	s_addc_u32 s5, s9, 0
	global_load_dwordx4 v[16:19], v232, s[4:5]
	global_load_dwordx4 v[20:23], v232, s[4:5] offset:1024
	global_load_dwordx4 v[24:27], v232, s[4:5] offset:2048
	global_load_dwordx4 v[28:31], v232, s[4:5] offset:3072
	s_waitcnt vmcnt(0)
	s_lshl_b32 s4, s6, 12
	s_add_u32 s4, s4, 0xc166000
	s_add_u32 s4, s4, s8
	s_addc_u32 s5, s9, 0
	global_load_dwordx4 v[32:35], v232, s[4:5]
	global_load_dwordx4 v[36:39], v232, s[4:5] offset:1024
	global_load_dwordx4 v[40:43], v232, s[4:5] offset:2048
	global_load_dwordx4 v[44:47], v232, s[4:5] offset:3072
	s_lshl_b32 s4, s6, 12
	s_add_u32 s4, s4, 0xc966000
	s_add_u32 s4, s4, s8
	s_addc_u32 s5, s9, 0
	global_load_dwordx4 v[48:51], v232, s[4:5]
	global_load_dwordx4 v[52:55], v232, s[4:5] offset:1024
	global_load_dwordx4 v[56:59], v232, s[4:5] offset:2048
	global_load_dwordx4 v[60:63], v232, s[4:5] offset:3072
	s_add_u32 s4, s10, 0x9000
	s_addc_u32 s5, s11, 0
	global_load_dwordx4 v[96:99], v232, s[4:5]
	global_load_dwordx4 v[100:103], v232, s[4:5] offset:1024
	global_load_dwordx4 v[104:107], v232, s[4:5] offset:2048
	global_load_dwordx4 v[108:111], v232, s[4:5] offset:3072
	s_add_u32 s4, s4, 0x1000
	s_addc_u32 s5, s5, 0
	global_load_dwordx4 v[112:115], v232, s[4:5]
	global_load_dwordx4 v[116:119], v232, s[4:5] offset:1024
	global_load_dwordx4 v[120:123], v232, s[4:5] offset:2048
	global_load_dwordx4 v[124:127], v232, s[4:5] offset:3072
	v_pk_add_f32 v[204:205], v[0:1], v[2:3]
	v_pk_add_f32 v[206:207], v[4:5], v[6:7]
	v_pk_add_f32 v[208:209], v[8:9], v[10:11]
	v_pk_add_f32 v[210:211], v[12:13], v[14:15]
	v_pk_add_f32 v[216:217], v[16:17], v[18:19]
	v_pk_add_f32 v[218:219], v[20:21], v[22:23]
	v_pk_add_f32 v[220:221], v[24:25], v[26:27]
	v_pk_add_f32 v[222:223], v[28:29], v[30:31]
	v_pk_add_f32 v[204:205], v[204:205], v[206:207]
	v_pk_add_f32 v[208:209], v[208:209], v[210:211]
	v_pk_add_f32 v[216:217], v[216:217], v[218:219]
	v_pk_add_f32 v[220:221], v[220:221], v[222:223]
	v_pk_add_f32 v[204:205], v[204:205], v[208:209]
	v_pk_add_f32 v[216:217], v[216:217], v[220:221]
	v_add_f32_e32 v204, v204, v205
	v_add_f32_e32 v216, v216, v217
	s_nop 1
	v_add_f32_dpp v204, v204, v204 row_ror:1 row_mask:0xf bank_mask:0xf bound_ctrl:1
	v_add_f32_dpp v216, v216, v216 row_ror:1 row_mask:0xf bank_mask:0xf bound_ctrl:1
	s_nop 0
	v_add_f32_dpp v204, v204, v204 row_ror:2 row_mask:0xf bank_mask:0xf bound_ctrl:1
	v_add_f32_dpp v216, v216, v216 row_ror:2 row_mask:0xf bank_mask:0xf bound_ctrl:1
	s_nop 0
	v_add_f32_dpp v204, v204, v204 row_ror:4 row_mask:0xf bank_mask:0xf bound_ctrl:1
	v_add_f32_dpp v216, v216, v216 row_ror:4 row_mask:0xf bank_mask:0xf bound_ctrl:1
	s_nop 0
	v_add_f32_dpp v204, v204, v204 row_ror:8 row_mask:0xf bank_mask:0xf bound_ctrl:1
	v_add_f32_dpp v216, v216, v216 row_ror:8 row_mask:0xf bank_mask:0xf bound_ctrl:1
	s_nop 0
	v_mov_b32_e32 v205, v204
	v_mov_b32_e32 v217, v216
	s_nop 1
	v_permlane16_swap_b32_e32 v204, v205
	v_permlane16_swap_b32_e32 v216, v217
	s_nop 0
	v_add_f32_e32 v204, v204, v205
	v_add_f32_e32 v216, v216, v217
	v_mov_b32_e32 v205, v204
	v_mov_b32_e32 v217, v216
	s_nop 1
	v_permlane32_swap_b32_e32 v204, v205
	v_permlane32_swap_b32_e32 v216, v217
	s_nop 0
	v_add_f32_e32 v204, v204, v205
	v_add_f32_e32 v216, v216, v217
	v_mul_f32_e32 v212, 0x3a800000, v204
	v_mul_f32_e32 v224, 0x3a800000, v216
	v_pk_add_f32 v[0:1], v[0:1], v[212:213] op_sel_hi:[1,0] neg_lo:[0,1] neg_hi:[0,1]
	v_pk_add_f32 v[2:3], v[2:3], v[212:213] op_sel_hi:[1,0] neg_lo:[0,1] neg_hi:[0,1]
	v_pk_add_f32 v[4:5], v[4:5], v[212:213] op_sel_hi:[1,0] neg_lo:[0,1] neg_hi:[0,1]
	v_pk_add_f32 v[6:7], v[6:7], v[212:213] op_sel_hi:[1,0] neg_lo:[0,1] neg_hi:[0,1]
	v_pk_add_f32 v[8:9], v[8:9], v[212:213] op_sel_hi:[1,0] neg_lo:[0,1] neg_hi:[0,1]
	v_pk_add_f32 v[10:11], v[10:11], v[212:213] op_sel_hi:[1,0] neg_lo:[0,1] neg_hi:[0,1]
	v_pk_add_f32 v[12:13], v[12:13], v[212:213] op_sel_hi:[1,0] neg_lo:[0,1] neg_hi:[0,1]
	v_pk_add_f32 v[14:15], v[14:15], v[212:213] op_sel_hi:[1,0] neg_lo:[0,1] neg_hi:[0,1]
	v_pk_add_f32 v[16:17], v[16:17], v[224:225] op_sel_hi:[1,0] neg_lo:[0,1] neg_hi:[0,1]
	v_pk_add_f32 v[18:19], v[18:19], v[224:225] op_sel_hi:[1,0] neg_lo:[0,1] neg_hi:[0,1]
	v_pk_add_f32 v[20:21], v[20:21], v[224:225] op_sel_hi:[1,0] neg_lo:[0,1] neg_hi:[0,1]
	v_pk_add_f32 v[22:23], v[22:23], v[224:225] op_sel_hi:[1,0] neg_lo:[0,1] neg_hi:[0,1]
	v_pk_add_f32 v[24:25], v[24:25], v[224:225] op_sel_hi:[1,0] neg_lo:[0,1] neg_hi:[0,1]
	v_pk_add_f32 v[26:27], v[26:27], v[224:225] op_sel_hi:[1,0] neg_lo:[0,1] neg_hi:[0,1]
	v_pk_add_f32 v[28:29], v[28:29], v[224:225] op_sel_hi:[1,0] neg_lo:[0,1] neg_hi:[0,1]
	v_pk_add_f32 v[30:31], v[30:31], v[224:225] op_sel_hi:[1,0] neg_lo:[0,1] neg_hi:[0,1]
	v_pk_mul_f32 v[204:205], v[0:1], v[0:1]
	v_pk_mul_f32 v[206:207], v[2:3], v[2:3]
	v_pk_mul_f32 v[216:217], v[16:17], v[16:17]
	v_pk_mul_f32 v[218:219], v[18:19], v[18:19]
	v_pk_fma_f32 v[204:205], v[4:5], v[4:5], v[204:205]
	v_pk_fma_f32 v[206:207], v[6:7], v[6:7], v[206:207]
	v_pk_fma_f32 v[216:217], v[20:21], v[20:21], v[216:217]
	v_pk_fma_f32 v[218:219], v[22:23], v[22:23], v[218:219]
	v_pk_fma_f32 v[204:205], v[8:9], v[8:9], v[204:205]
	v_pk_fma_f32 v[206:207], v[10:11], v[10:11], v[206:207]
	v_pk_fma_f32 v[216:217], v[24:25], v[24:25], v[216:217]
	v_pk_fma_f32 v[218:219], v[26:27], v[26:27], v[218:219]
	v_pk_fma_f32 v[204:205], v[12:13], v[12:13], v[204:205]
	v_pk_fma_f32 v[206:207], v[14:15], v[14:15], v[206:207]
	v_pk_fma_f32 v[216:217], v[28:29], v[28:29], v[216:217]
	v_pk_fma_f32 v[218:219], v[30:31], v[30:31], v[218:219]
	v_pk_add_f32 v[204:205], v[204:205], v[206:207]
	v_pk_add_f32 v[216:217], v[216:217], v[218:219]
	v_add_f32_e32 v204, v204, v205
	v_add_f32_e32 v216, v216, v217
	s_nop 1
	v_add_f32_dpp v204, v204, v204 row_ror:1 row_mask:0xf bank_mask:0xf bound_ctrl:1
	v_add_f32_dpp v216, v216, v216 row_ror:1 row_mask:0xf bank_mask:0xf bound_ctrl:1
	s_nop 0
	v_add_f32_dpp v204, v204, v204 row_ror:2 row_mask:0xf bank_mask:0xf bound_ctrl:1
	v_add_f32_dpp v216, v216, v216 row_ror:2 row_mask:0xf bank_mask:0xf bound_ctrl:1
	s_nop 0
	v_add_f32_dpp v204, v204, v204 row_ror:4 row_mask:0xf bank_mask:0xf bound_ctrl:1
	v_add_f32_dpp v216, v216, v216 row_ror:4 row_mask:0xf bank_mask:0xf bound_ctrl:1
	s_nop 0
	v_add_f32_dpp v204, v204, v204 row_ror:8 row_mask:0xf bank_mask:0xf bound_ctrl:1
	v_add_f32_dpp v216, v216, v216 row_ror:8 row_mask:0xf bank_mask:0xf bound_ctrl:1
	s_nop 0
	v_mov_b32_e32 v205, v204
	v_mov_b32_e32 v217, v216
	s_nop 1
	v_permlane16_swap_b32_e32 v204, v205
	v_permlane16_swap_b32_e32 v216, v217
	s_nop 0
	v_add_f32_e32 v204, v204, v205
	v_add_f32_e32 v216, v216, v217
	v_mov_b32_e32 v205, v204
	v_mov_b32_e32 v217, v216
	s_nop 1
	v_permlane32_swap_b32_e32 v204, v205
	v_permlane32_swap_b32_e32 v216, v217
	s_nop 0
	v_add_f32_e32 v204, v204, v205
	v_add_f32_e32 v216, v216, v217
	v_mov_b32_e32 v205, 0x3727c5ac
	v_fmac_f32_e32 v205, 0x3a800000, v204
	v_mov_b32_e32 v217, 0x3727c5ac
	v_fmac_f32_e32 v217, 0x3a800000, v216
	v_mul_f32_e32 v206, 0x4b800000, v205
	s_mov_b32 s4, 0x800000
	v_cmp_gt_f32_e32 vcc, s4, v205
	s_nop 1
	v_cndmask_b32_e32 v205, v205, v206, vcc
	v_rsq_f32_e32 v205, v205
	s_nop 0
	v_mul_f32_e32 v206, 0x45800000, v205
	v_cndmask_b32_e32 v214, v205, v206, vcc
	v_mul_f32_e32 v218, 0x4b800000, v217
	s_mov_b32 s4, 0x800000
	v_cmp_gt_f32_e32 vcc, s4, v217
	s_nop 1
	v_cndmask_b32_e32 v217, v217, v218, vcc
	v_rsq_f32_e32 v217, v217
	s_nop 0
	v_mul_f32_e32 v218, 0x45800000, v217
	v_cndmask_b32_e32 v226, v217, v218, vcc
	v_pk_mul_f32 v[0:1], v[0:1], v[214:215] op_sel_hi:[1,0]
	v_pk_mul_f32 v[2:3], v[2:3], v[214:215] op_sel_hi:[1,0]
	v_pk_mul_f32 v[4:5], v[4:5], v[214:215] op_sel_hi:[1,0]
	v_pk_mul_f32 v[6:7], v[6:7], v[214:215] op_sel_hi:[1,0]
	v_pk_mul_f32 v[8:9], v[8:9], v[214:215] op_sel_hi:[1,0]
	v_pk_mul_f32 v[10:11], v[10:11], v[214:215] op_sel_hi:[1,0]
	v_pk_mul_f32 v[12:13], v[12:13], v[214:215] op_sel_hi:[1,0]
	v_pk_mul_f32 v[14:15], v[14:15], v[214:215] op_sel_hi:[1,0]
	v_pk_mul_f32 v[16:17], v[16:17], v[226:227] op_sel_hi:[1,0]
	v_pk_mul_f32 v[18:19], v[18:19], v[226:227] op_sel_hi:[1,0]
	v_pk_mul_f32 v[20:21], v[20:21], v[226:227] op_sel_hi:[1,0]
	v_pk_mul_f32 v[22:23], v[22:23], v[226:227] op_sel_hi:[1,0]
	v_pk_mul_f32 v[24:25], v[24:25], v[226:227] op_sel_hi:[1,0]
	v_pk_mul_f32 v[26:27], v[26:27], v[226:227] op_sel_hi:[1,0]
	v_pk_mul_f32 v[28:29], v[28:29], v[226:227] op_sel_hi:[1,0]
	v_pk_mul_f32 v[30:31], v[30:31], v[226:227] op_sel_hi:[1,0]
	v_pk_fma_f32 v[0:1], v[136:137], v[0:1], v[152:153]
	v_pk_fma_f32 v[2:3], v[138:139], v[2:3], v[154:155]
	v_pk_fma_f32 v[4:5], v[140:141], v[4:5], v[156:157]
	v_pk_fma_f32 v[6:7], v[142:143], v[6:7], v[158:159]
	v_pk_fma_f32 v[8:9], v[144:145], v[8:9], v[160:161]
	v_pk_fma_f32 v[10:11], v[146:147], v[10:11], v[162:163]
	v_pk_fma_f32 v[12:13], v[148:149], v[12:13], v[164:165]
	v_pk_fma_f32 v[14:15], v[150:151], v[14:15], v[166:167]
	v_pk_fma_f32 v[16:17], v[136:137], v[16:17], v[152:153]
	v_pk_fma_f32 v[18:19], v[138:139], v[18:19], v[154:155]
	v_pk_fma_f32 v[20:21], v[140:141], v[20:21], v[156:157]
	v_pk_fma_f32 v[22:23], v[142:143], v[22:23], v[158:159]
	v_pk_fma_f32 v[24:25], v[144:145], v[24:25], v[160:161]
	v_pk_fma_f32 v[26:27], v[146:147], v[26:27], v[162:163]
	v_pk_fma_f32 v[28:29], v[148:149], v[28:29], v[164:165]
	v_pk_fma_f32 v[30:31], v[150:151], v[30:31], v[166:167]
	v_mov_b32_e32 v228, v212
	v_mov_b32_e32 v229, v214
	v_mov_b32_e32 v168, v224
	v_mov_b32_e32 v169, v226
	s_cmp_eq_u32 s57, 1
	s_cbranch_scc1 .Llna_last0
	v_add_f32_e32 v80, 1.0, v80
	v_add_f32_e32 v81, 1.0, v81
	v_add_f32_e32 v82, 1.0, v82
	v_add_f32_e32 v83, 1.0, v83
	v_add_f32_e32 v84, 1.0, v84
	v_add_f32_e32 v85, 1.0, v85
	v_add_f32_e32 v86, 1.0, v86
	v_add_f32_e32 v87, 1.0, v87
	v_add_f32_e32 v88, 1.0, v88
	v_add_f32_e32 v89, 1.0, v89
	v_add_f32_e32 v90, 1.0, v90
	v_add_f32_e32 v91, 1.0, v91
	v_add_f32_e32 v92, 1.0, v92
	v_add_f32_e32 v93, 1.0, v93
	v_add_f32_e32 v94, 1.0, v94
	v_add_f32_e32 v95, 1.0, v95
	v_pk_fma_f32 v[204:205], v[80:81], v[0:1], v[64:65]
	v_pk_fma_f32 v[206:207], v[82:83], v[2:3], v[66:67]
	v_pk_fma_f32 v[208:209], v[84:85], v[4:5], v[68:69]
	v_pk_fma_f32 v[210:211], v[86:87], v[6:7], v[70:71]
	v_pk_fma_f32 v[212:213], v[88:89], v[8:9], v[72:73]
	v_pk_fma_f32 v[214:215], v[90:91], v[10:11], v[74:75]
	v_pk_fma_f32 v[216:217], v[92:93], v[12:13], v[76:77]
	v_pk_fma_f32 v[218:219], v[94:95], v[14:15], v[78:79]
	v_cvt_pk_bf16_f32 v220, v204, v205
	v_cvt_pk_bf16_f32 v221, v206, v207
	v_cvt_pk_bf16_f32 v222, v208, v209
	v_cvt_pk_bf16_f32 v223, v210, v211
	v_cvt_pk_bf16_f32 v224, v212, v213
	v_cvt_pk_bf16_f32 v225, v214, v215
	v_cvt_pk_bf16_f32 v226, v216, v217
	v_cvt_pk_bf16_f32 v227, v218, v219
	s_mul_i32 s4, s6, 0x880
	s_add_u32 s4, s4, 0xe166000
	s_add_u32 s4, s4, s8
	s_addc_u32 s5, s9, 0
	global_store_dwordx2 v233, v[220:221], s[4:5]
	global_store_dwordx2 v233, v[222:223], s[4:5] offset:512
	global_store_dwordx2 v233, v[224:225], s[4:5] offset:1024
	global_store_dwordx2 v233, v[226:227], s[4:5] offset:1536
	s_mov_b64 s[12:13], exec
	s_mov_b64 exec, 1
	global_store_dwordx2 v129, v[228:229], s[4:5] offset:2048
	s_mov_b64 exec, s[12:13]
	v_pk_fma_f32 v[204:205], v[80:81], v[16:17], v[64:65]
	v_pk_fma_f32 v[206:207], v[82:83], v[18:19], v[66:67]
	v_pk_fma_f32 v[208:209], v[84:85], v[20:21], v[68:69]
	v_pk_fma_f32 v[210:211], v[86:87], v[22:23], v[70:71]
	v_pk_fma_f32 v[212:213], v[88:89], v[24:25], v[72:73]
	v_pk_fma_f32 v[214:215], v[90:91], v[26:27], v[74:75]
	v_pk_fma_f32 v[216:217], v[92:93], v[28:29], v[76:77]
	v_pk_fma_f32 v[218:219], v[94:95], v[30:31], v[78:79]
	v_cvt_pk_bf16_f32 v220, v204, v205
	v_cvt_pk_bf16_f32 v221, v206, v207
	v_cvt_pk_bf16_f32 v222, v208, v209
	v_cvt_pk_bf16_f32 v223, v210, v211
	v_cvt_pk_bf16_f32 v224, v212, v213
	v_cvt_pk_bf16_f32 v225, v214, v215
	v_cvt_pk_bf16_f32 v226, v216, v217
	v_cvt_pk_bf16_f32 v227, v218, v219
	s_mul_i32 s4, s6, 0x880
	s_add_u32 s4, s4, 0xe5a6000
	s_add_u32 s4, s4, s8
	s_addc_u32 s5, s9, 0
	global_store_dwordx2 v233, v[220:221], s[4:5]
	global_store_dwordx2 v233, v[222:223], s[4:5] offset:512
	global_store_dwordx2 v233, v[224:225], s[4:5] offset:1024
	global_store_dwordx2 v233, v[226:227], s[4:5] offset:1536
	s_mov_b64 s[12:13], exec
	s_mov_b64 exec, 1
	global_store_dwordx2 v129, v[168:169], s[4:5] offset:2048
	s_mov_b64 exec, s[12:13]
	s_branch .Llna_join0

.LBB0_90:
	v_readlane_b32 s2, v235, 48
	s_cmp_lt_i32 s2, 7
	s_mov_b64 s[34:35], -1
	s_cbranch_scc1 .LBB0_121
	v_readlane_b32 s2, v235, 48
	s_cmp_gt_i32 s2, 7
	s_cbranch_scc0 .LBB0_104
	s_waitcnt lgkmcnt(0)
	v_mov_b32_e32 v34, v170
	v_mov_b32_e32 v0, v170
	v_readlane_b32 s4, v235, 17
	v_ashrrev_i32_e32 v33, 6, v0
	s_nop 0
	v_add_u32_e32 v32, s4, v33
	s_movk_i32 s4, 0x3000
	v_cmp_gt_i32_e32 vcc, s4, v32
	s_and_saveexec_b64 s[36:37], vcc
	s_cbranch_execz .LBB0_103
	v_readlane_b32 s4, v235, 33
	s_cmp_lg_u32 s4, 0x200
	s_cbranch_scc1 .Llnb_orig
	v_and_b32_e32 v232, 63, v170
	v_lshlrev_b32_e32 v233, 3, v232
	v_lshlrev_b32_e32 v232, 4, v232
	v_lshrrev_b32_e32 v231, 6, v170
	s_nop 0
	v_readfirstlane_b32 s6, v231
	v_readlane_b32 s7, v237, 0
	s_lshl_b32 s7, s7, 2
	s_add_u32 s6, s6, s7
	v_readlane_b32 s8, v235, 34
	v_readlane_b32 s9, v235, 35
	v_readlane_b32 s7, v235, 44
	s_mul_i32 s10, s7, 3
	s_add_u32 s10, s10, 1
	s_lshl_b32 s10, s10, 12
	v_readlane_b32 s4, v237, 25
	v_readlane_b32 s5, v237, 26
	s_add_u32 s4, s4, s10
	s_addc_u32 s5, s5, 0
	global_load_dwordx4 v[136:139], v232, s[4:5]
	global_load_dwordx4 v[140:143], v232, s[4:5] offset:1024
	global_load_dwordx4 v[144:147], v232, s[4:5] offset:2048
	global_load_dwordx4 v[148:151], v232, s[4:5] offset:3072
	v_readlane_b32 s4, v237, 27
	v_readlane_b32 s5, v237, 28
	s_add_u32 s4, s4, s10
	s_addc_u32 s5, s5, 0
	global_load_dwordx4 v[152:155], v232, s[4:5]
	global_load_dwordx4 v[156:159], v232, s[4:5] offset:1024
	global_load_dwordx4 v[160:163], v232, s[4:5] offset:2048
	global_load_dwordx4 v[164:167], v232, s[4:5] offset:3072
	s_mov_b32 s11, s7
	s_mul_i32 s11, s11, 0x1b000
	s_add_u32 s11, s11, 0xb0fe000
	s_add_u32 s10, s8, s11
	s_addc_u32 s11, s9, 0
	s_add_u32 s4, s10, 0x0
	s_addc_u32 s5, s11, 0
	global_load_dwordx4 v[64:67], v232, s[4:5]
	global_load_dwordx4 v[68:71], v232, s[4:5] offset:1024
	global_load_dwordx4 v[72:75], v232, s[4:5] offset:2048
	global_load_dwordx4 v[76:79], v232, s[4:5] offset:3072
	s_add_u32 s4, s4, 0x1000
	s_addc_u32 s5, s5, 0
	global_load_dwordx4 v[80:83], v232, s[4:5]
	global_load_dwordx4 v[84:87], v232, s[4:5] offset:1024
	global_load_dwordx4 v[88:91], v232, s[4:5] offset:2048
	global_load_dwordx4 v[92:95], v232, s[4:5] offset:3072
	s_lshl_b32 s4, s6, 12
	s_add_u32 s4, s4, 0xb166000
	s_add_u32 s4, s4, s8
	s_addc_u32 s5, s9, 0
	global_load_dwordx4 v[0:3], v232, s[4:5]
	global_load_dwordx4 v[4:7], v232, s[4:5] offset:1024
	global_load_dwordx4 v[8:11], v232, s[4:5] offset:2048
	global_load_dwordx4 v[12:15], v232, s[4:5] offset:3072
	s_lshl_b32 s4, s6, 12
	s_add_u32 s4, s4, 0xb966000
	s_add_u32 s4, s4, s8
	s_addc_u32 s5, s9, 0
	global_load_dwordx4 v[16:19], v232, s[4:5]
	global_load_dwordx4 v[20:23], v232, s[4:5] offset:1024
	global_load_dwordx4 v[24:27], v232, s[4:5] offset:2048
	global_load_dwordx4 v[28:31], v232, s[4:5] offset:3072
	s_waitcnt vmcnt(0)
	s_lshl_b32 s4, s6, 12
	s_add_u32 s4, s4, 0xc166000
	s_add_u32 s4, s4, s8
	s_addc_u32 s5, s9, 0
	global_load_dwordx4 v[32:35], v232, s[4:5]
	global_load_dwordx4 v[36:39], v232, s[4:5] offset:1024
	global_load_dwordx4 v[40:43], v232, s[4:5] offset:2048
	global_load_dwordx4 v[44:47], v232, s[4:5] offset:3072
	s_lshl_b32 s4, s6, 12
	s_add_u32 s4, s4, 0xc966000
	s_add_u32 s4, s4, s8
	s_addc_u32 s5, s9, 0
	global_load_dwordx4 v[48:51], v232, s[4:5]
	global_load_dwordx4 v[52:55], v232, s[4:5] offset:1024
	global_load_dwordx4 v[56:59], v232, s[4:5] offset:2048
	global_load_dwordx4 v[60:63], v232, s[4:5] offset:3072
	s_add_u32 s4, s10, 0x9000
	s_addc_u32 s5, s11, 0
	global_load_dwordx4 v[96:99], v232, s[4:5]
	global_load_dwordx4 v[100:103], v232, s[4:5] offset:1024
	global_load_dwordx4 v[104:107], v232, s[4:5] offset:2048
	global_load_dwordx4 v[108:111], v232, s[4:5] offset:3072
	s_add_u32 s4, s4, 0x1000
	s_addc_u32 s5, s5, 0
	global_load_dwordx4 v[112:115], v232, s[4:5]
	global_load_dwordx4 v[116:119], v232, s[4:5] offset:1024
	global_load_dwordx4 v[120:123], v232, s[4:5] offset:2048
	global_load_dwordx4 v[124:127], v232, s[4:5] offset:3072
	v_pk_add_f32 v[204:205], v[0:1], v[2:3]
	v_pk_add_f32 v[206:207], v[4:5], v[6:7]
	v_pk_add_f32 v[208:209], v[8:9], v[10:11]
	v_pk_add_f32 v[210:211], v[12:13], v[14:15]
	v_pk_add_f32 v[216:217], v[16:17], v[18:19]
	v_pk_add_f32 v[218:219], v[20:21], v[22:23]
	v_pk_add_f32 v[220:221], v[24:25], v[26:27]
	v_pk_add_f32 v[222:223], v[28:29], v[30:31]
	v_pk_add_f32 v[204:205], v[204:205], v[206:207]
	v_pk_add_f32 v[208:209], v[208:209], v[210:211]
	v_pk_add_f32 v[216:217], v[216:217], v[218:219]
	v_pk_add_f32 v[220:221], v[220:221], v[222:223]
	v_pk_add_f32 v[204:205], v[204:205], v[208:209]
	v_pk_add_f32 v[216:217], v[216:217], v[220:221]
	v_add_f32_e32 v204, v204, v205
	v_add_f32_e32 v216, v216, v217
	s_nop 1
	v_add_f32_dpp v204, v204, v204 row_ror:1 row_mask:0xf bank_mask:0xf bound_ctrl:1
	v_add_f32_dpp v216, v216, v216 row_ror:1 row_mask:0xf bank_mask:0xf bound_ctrl:1
	s_nop 0
	v_add_f32_dpp v204, v204, v204 row_ror:2 row_mask:0xf bank_mask:0xf bound_ctrl:1
	v_add_f32_dpp v216, v216, v216 row_ror:2 row_mask:0xf bank_mask:0xf bound_ctrl:1
	s_nop 0
	v_add_f32_dpp v204, v204, v204 row_ror:4 row_mask:0xf bank_mask:0xf bound_ctrl:1
	v_add_f32_dpp v216, v216, v216 row_ror:4 row_mask:0xf bank_mask:0xf bound_ctrl:1
	s_nop 0
	v_add_f32_dpp v204, v204, v204 row_ror:8 row_mask:0xf bank_mask:0xf bound_ctrl:1
	v_add_f32_dpp v216, v216, v216 row_ror:8 row_mask:0xf bank_mask:0xf bound_ctrl:1
	s_nop 0
	v_mov_b32_e32 v205, v204
	v_mov_b32_e32 v217, v216
	s_nop 1
	v_permlane16_swap_b32_e32 v204, v205
	v_permlane16_swap_b32_e32 v216, v217
	s_nop 0
	v_add_f32_e32 v204, v204, v205
	v_add_f32_e32 v216, v216, v217
	v_mov_b32_e32 v205, v204
	v_mov_b32_e32 v217, v216
	s_nop 1
	v_permlane32_swap_b32_e32 v204, v205
	v_permlane32_swap_b32_e32 v216, v217
	s_nop 0
	v_add_f32_e32 v204, v204, v205
	v_add_f32_e32 v216, v216, v217
	v_mul_f32_e32 v212, 0x3a800000, v204
	v_mul_f32_e32 v224, 0x3a800000, v216
	v_pk_add_f32 v[0:1], v[0:1], v[212:213] op_sel_hi:[1,0] neg_lo:[0,1] neg_hi:[0,1]
	v_pk_add_f32 v[2:3], v[2:3], v[212:213] op_sel_hi:[1,0] neg_lo:[0,1] neg_hi:[0,1]
	v_pk_add_f32 v[4:5], v[4:5], v[212:213] op_sel_hi:[1,0] neg_lo:[0,1] neg_hi:[0,1]
	v_pk_add_f32 v[6:7], v[6:7], v[212:213] op_sel_hi:[1,0] neg_lo:[0,1] neg_hi:[0,1]
	v_pk_add_f32 v[8:9], v[8:9], v[212:213] op_sel_hi:[1,0] neg_lo:[0,1] neg_hi:[0,1]
	v_pk_add_f32 v[10:11], v[10:11], v[212:213] op_sel_hi:[1,0] neg_lo:[0,1] neg_hi:[0,1]
	v_pk_add_f32 v[12:13], v[12:13], v[212:213] op_sel_hi:[1,0] neg_lo:[0,1] neg_hi:[0,1]
	v_pk_add_f32 v[14:15], v[14:15], v[212:213] op_sel_hi:[1,0] neg_lo:[0,1] neg_hi:[0,1]
	v_pk_add_f32 v[16:17], v[16:17], v[224:225] op_sel_hi:[1,0] neg_lo:[0,1] neg_hi:[0,1]
	v_pk_add_f32 v[18:19], v[18:19], v[224:225] op_sel_hi:[1,0] neg_lo:[0,1] neg_hi:[0,1]
	v_pk_add_f32 v[20:21], v[20:21], v[224:225] op_sel_hi:[1,0] neg_lo:[0,1] neg_hi:[0,1]
	v_pk_add_f32 v[22:23], v[22:23], v[224:225] op_sel_hi:[1,0] neg_lo:[0,1] neg_hi:[0,1]
	v_pk_add_f32 v[24:25], v[24:25], v[224:225] op_sel_hi:[1,0] neg_lo:[0,1] neg_hi:[0,1]
	v_pk_add_f32 v[26:27], v[26:27], v[224:225] op_sel_hi:[1,0] neg_lo:[0,1] neg_hi:[0,1]
	v_pk_add_f32 v[28:29], v[28:29], v[224:225] op_sel_hi:[1,0] neg_lo:[0,1] neg_hi:[0,1]
	v_pk_add_f32 v[30:31], v[30:31], v[224:225] op_sel_hi:[1,0] neg_lo:[0,1] neg_hi:[0,1]
	v_pk_mul_f32 v[204:205], v[0:1], v[0:1]
	v_pk_mul_f32 v[206:207], v[2:3], v[2:3]
	v_pk_mul_f32 v[216:217], v[16:17], v[16:17]
	v_pk_mul_f32 v[218:219], v[18:19], v[18:19]
	v_pk_fma_f32 v[204:205], v[4:5], v[4:5], v[204:205]
	v_pk_fma_f32 v[206:207], v[6:7], v[6:7], v[206:207]
	v_pk_fma_f32 v[216:217], v[20:21], v[20:21], v[216:217]
	v_pk_fma_f32 v[218:219], v[22:23], v[22:23], v[218:219]
	v_pk_fma_f32 v[204:205], v[8:9], v[8:9], v[204:205]
	v_pk_fma_f32 v[206:207], v[10:11], v[10:11], v[206:207]
	v_pk_fma_f32 v[216:217], v[24:25], v[24:25], v[216:217]
	v_pk_fma_f32 v[218:219], v[26:27], v[26:27], v[218:219]
	v_pk_fma_f32 v[204:205], v[12:13], v[12:13], v[204:205]
	v_pk_fma_f32 v[206:207], v[14:15], v[14:15], v[206:207]
	v_pk_fma_f32 v[216:217], v[28:29], v[28:29], v[216:217]
	v_pk_fma_f32 v[218:219], v[30:31], v[30:31], v[218:219]
	v_pk_add_f32 v[204:205], v[204:205], v[206:207]
	v_pk_add_f32 v[216:217], v[216:217], v[218:219]
	v_add_f32_e32 v204, v204, v205
	v_add_f32_e32 v216, v216, v217
	s_nop 1
	v_add_f32_dpp v204, v204, v204 row_ror:1 row_mask:0xf bank_mask:0xf bound_ctrl:1
	v_add_f32_dpp v216, v216, v216 row_ror:1 row_mask:0xf bank_mask:0xf bound_ctrl:1
	s_nop 0
	v_add_f32_dpp v204, v204, v204 row_ror:2 row_mask:0xf bank_mask:0xf bound_ctrl:1
	v_add_f32_dpp v216, v216, v216 row_ror:2 row_mask:0xf bank_mask:0xf bound_ctrl:1
	s_nop 0
	v_add_f32_dpp v204, v204, v204 row_ror:4 row_mask:0xf bank_mask:0xf bound_ctrl:1
	v_add_f32_dpp v216, v216, v216 row_ror:4 row_mask:0xf bank_mask:0xf bound_ctrl:1
	s_nop 0
	v_add_f32_dpp v204, v204, v204 row_ror:8 row_mask:0xf bank_mask:0xf bound_ctrl:1
	v_add_f32_dpp v216, v216, v216 row_ror:8 row_mask:0xf bank_mask:0xf bound_ctrl:1
	s_nop 0
	v_mov_b32_e32 v205, v204
	v_mov_b32_e32 v217, v216
	s_nop 1
	v_permlane16_swap_b32_e32 v204, v205
	v_permlane16_swap_b32_e32 v216, v217
	s_nop 0
	v_add_f32_e32 v204, v204, v205
	v_add_f32_e32 v216, v216, v217
	v_mov_b32_e32 v205, v204
	v_mov_b32_e32 v217, v216
	s_nop 1
	v_permlane32_swap_b32_e32 v204, v205
	v_permlane32_swap_b32_e32 v216, v217
	s_nop 0
	v_add_f32_e32 v204, v204, v205
	v_add_f32_e32 v216, v216, v217
	v_mov_b32_e32 v205, 0x3727c5ac
	v_fmac_f32_e32 v205, 0x3a800000, v204
	v_mov_b32_e32 v217, 0x3727c5ac
	v_fmac_f32_e32 v217, 0x3a800000, v216
	v_mul_f32_e32 v206, 0x4b800000, v205
	s_mov_b32 s4, 0x800000
	v_cmp_gt_f32_e32 vcc, s4, v205
	s_nop 1
	v_cndmask_b32_e32 v205, v205, v206, vcc
	v_rsq_f32_e32 v205, v205
	s_nop 0
	v_mul_f32_e32 v206, 0x45800000, v205
	v_cndmask_b32_e32 v214, v205, v206, vcc
	v_mul_f32_e32 v218, 0x4b800000, v217
	s_mov_b32 s4, 0x800000
	v_cmp_gt_f32_e32 vcc, s4, v217
	s_nop 1
	v_cndmask_b32_e32 v217, v217, v218, vcc
	v_rsq_f32_e32 v217, v217
	s_nop 0
	v_mul_f32_e32 v218, 0x45800000, v217
	v_cndmask_b32_e32 v226, v217, v218, vcc
	v_pk_mul_f32 v[0:1], v[0:1], v[214:215] op_sel_hi:[1,0]
	v_pk_mul_f32 v[2:3], v[2:3], v[214:215] op_sel_hi:[1,0]
	v_pk_mul_f32 v[4:5], v[4:5], v[214:215] op_sel_hi:[1,0]
	v_pk_mul_f32 v[6:7], v[6:7], v[214:215] op_sel_hi:[1,0]
	v_pk_mul_f32 v[8:9], v[8:9], v[214:215] op_sel_hi:[1,0]
	v_pk_mul_f32 v[10:11], v[10:11], v[214:215] op_sel_hi:[1,0]
	v_pk_mul_f32 v[12:13], v[12:13], v[214:215] op_sel_hi:[1,0]
	v_pk_mul_f32 v[14:15], v[14:15], v[214:215] op_sel_hi:[1,0]
	v_pk_mul_f32 v[16:17], v[16:17], v[226:227] op_sel_hi:[1,0]
	v_pk_mul_f32 v[18:19], v[18:19], v[226:227] op_sel_hi:[1,0]
	v_pk_mul_f32 v[20:21], v[20:21], v[226:227] op_sel_hi:[1,0]
	v_pk_mul_f32 v[22:23], v[22:23], v[226:227] op_sel_hi:[1,0]
	v_pk_mul_f32 v[24:25], v[24:25], v[226:227] op_sel_hi:[1,0]
	v_pk_mul_f32 v[26:27], v[26:27], v[226:227] op_sel_hi:[1,0]
	v_pk_mul_f32 v[28:29], v[28:29], v[226:227] op_sel_hi:[1,0]
	v_pk_mul_f32 v[30:31], v[30:31], v[226:227] op_sel_hi:[1,0]
	v_pk_fma_f32 v[0:1], v[136:137], v[0:1], v[152:153]
	v_pk_fma_f32 v[2:3], v[138:139], v[2:3], v[154:155]
	v_pk_fma_f32 v[4:5], v[140:141], v[4:5], v[156:157]
	v_pk_fma_f32 v[6:7], v[142:143], v[6:7], v[158:159]
	v_pk_fma_f32 v[8:9], v[144:145], v[8:9], v[160:161]
	v_pk_fma_f32 v[10:11], v[146:147], v[10:11], v[162:163]
	v_pk_fma_f32 v[12:13], v[148:149], v[12:13], v[164:165]
	v_pk_fma_f32 v[14:15], v[150:151], v[14:15], v[166:167]
	v_pk_fma_f32 v[16:17], v[136:137], v[16:17], v[152:153]
	v_pk_fma_f32 v[18:19], v[138:139], v[18:19], v[154:155]
	v_pk_fma_f32 v[20:21], v[140:141], v[20:21], v[156:157]
	v_pk_fma_f32 v[22:23], v[142:143], v[22:23], v[158:159]
	v_pk_fma_f32 v[24:25], v[144:145], v[24:25], v[160:161]
	v_pk_fma_f32 v[26:27], v[146:147], v[26:27], v[162:163]
	v_pk_fma_f32 v[28:29], v[148:149], v[28:29], v[164:165]
	v_pk_fma_f32 v[30:31], v[150:151], v[30:31], v[166:167]
	v_mov_b32_e32 v228, v212
	v_mov_b32_e32 v229, v214
	v_mov_b32_e32 v168, v224
	v_mov_b32_e32 v169, v226
	v_add_f32_e32 v80, 1.0, v80
	v_add_f32_e32 v81, 1.0, v81
	v_add_f32_e32 v82, 1.0, v82
	v_add_f32_e32 v83, 1.0, v83
	v_add_f32_e32 v84, 1.0, v84
	v_add_f32_e32 v85, 1.0, v85
	v_add_f32_e32 v86, 1.0, v86
	v_add_f32_e32 v87, 1.0, v87
	v_add_f32_e32 v88, 1.0, v88
	v_add_f32_e32 v89, 1.0, v89
	v_add_f32_e32 v90, 1.0, v90
	v_add_f32_e32 v91, 1.0, v91
	v_add_f32_e32 v92, 1.0, v92
	v_add_f32_e32 v93, 1.0, v93
	v_add_f32_e32 v94, 1.0, v94
	v_add_f32_e32 v95, 1.0, v95
	v_pk_fma_f32 v[204:205], v[80:81], v[0:1], v[64:65]
	v_pk_fma_f32 v[206:207], v[82:83], v[2:3], v[66:67]
	v_pk_fma_f32 v[208:209], v[84:85], v[4:5], v[68:69]
	v_pk_fma_f32 v[210:211], v[86:87], v[6:7], v[70:71]
	v_pk_fma_f32 v[212:213], v[88:89], v[8:9], v[72:73]
	v_pk_fma_f32 v[214:215], v[90:91], v[10:11], v[74:75]
	v_pk_fma_f32 v[216:217], v[92:93], v[12:13], v[76:77]
	v_pk_fma_f32 v[218:219], v[94:95], v[14:15], v[78:79]
	v_cvt_pk_bf16_f32 v220, v204, v205
	v_cvt_pk_bf16_f32 v221, v206, v207
	v_cvt_pk_bf16_f32 v222, v208, v209
	v_cvt_pk_bf16_f32 v223, v210, v211
	v_cvt_pk_bf16_f32 v224, v212, v213
	v_cvt_pk_bf16_f32 v225, v214, v215
	v_cvt_pk_bf16_f32 v226, v216, v217
	v_cvt_pk_bf16_f32 v227, v218, v219
	s_mul_i32 s4, s6, 0x880
	s_add_u32 s4, s4, 0xe166000
	s_add_u32 s4, s4, s8
	s_addc_u32 s5, s9, 0
	global_store_dwordx2 v233, v[220:221], s[4:5]
	global_store_dwordx2 v233, v[222:223], s[4:5] offset:512
	global_store_dwordx2 v233, v[224:225], s[4:5] offset:1024
	global_store_dwordx2 v233, v[226:227], s[4:5] offset:1536
	s_mov_b64 s[12:13], exec
	s_mov_b64 exec, 1
	global_store_dwordx2 v129, v[228:229], s[4:5] offset:2048
	s_mov_b64 exec, s[12:13]
	v_pk_fma_f32 v[204:205], v[80:81], v[16:17], v[64:65]
	v_pk_fma_f32 v[206:207], v[82:83], v[18:19], v[66:67]
	v_pk_fma_f32 v[208:209], v[84:85], v[20:21], v[68:69]
	v_pk_fma_f32 v[210:211], v[86:87], v[22:23], v[70:71]
	v_pk_fma_f32 v[212:213], v[88:89], v[24:25], v[72:73]
	v_pk_fma_f32 v[214:215], v[90:91], v[26:27], v[74:75]
	v_pk_fma_f32 v[216:217], v[92:93], v[28:29], v[76:77]
	v_pk_fma_f32 v[218:219], v[94:95], v[30:31], v[78:79]
	v_cvt_pk_bf16_f32 v220, v204, v205
	v_cvt_pk_bf16_f32 v221, v206, v207
	v_cvt_pk_bf16_f32 v222, v208, v209
	v_cvt_pk_bf16_f32 v223, v210, v211
	v_cvt_pk_bf16_f32 v224, v212, v213
	v_cvt_pk_bf16_f32 v225, v214, v215
	v_cvt_pk_bf16_f32 v226, v216, v217
	v_cvt_pk_bf16_f32 v227, v218, v219
	s_mul_i32 s4, s6, 0x880
	s_add_u32 s4, s4, 0xe5a6000
	s_add_u32 s4, s4, s8
	s_addc_u32 s5, s9, 0
	global_store_dwordx2 v233, v[220:221], s[4:5]
	global_store_dwordx2 v233, v[222:223], s[4:5] offset:512
	global_store_dwordx2 v233, v[224:225], s[4:5] offset:1024
	global_store_dwordx2 v233, v[226:227], s[4:5] offset:1536
	s_mov_b64 s[12:13], exec
	s_mov_b64 exec, 1
	global_store_dwordx2 v129, v[168:169], s[4:5] offset:2048
	s_mov_b64 exec, s[12:13]
	s_lshl_b32 s4, s6, 12
	s_add_u32 s4, s4, 0xd166000
	s_add_u32 s4, s4, s8
	s_addc_u32 s5, s9, 0
	global_load_dwordx4 v[0:3], v232, s[4:5]
	global_load_dwordx4 v[4:7], v232, s[4:5] offset:1024
	global_load_dwordx4 v[8:11], v232, s[4:5] offset:2048
	global_load_dwordx4 v[12:15], v232, s[4:5] offset:3072
	s_lshl_b32 s4, s6, 12
	s_add_u32 s4, s4, 0xd966000
	s_add_u32 s4, s4, s8
	s_addc_u32 s5, s9, 0
	global_load_dwordx4 v[16:19], v232, s[4:5]
	global_load_dwordx4 v[20:23], v232, s[4:5] offset:1024
	global_load_dwordx4 v[24:27], v232, s[4:5] offset:2048
	global_load_dwordx4 v[28:31], v232, s[4:5] offset:3072
	s_add_u32 s4, s10, 0x12000
	s_addc_u32 s5, s11, 0
	global_load_dwordx4 v[64:67], v232, s[4:5]
	global_load_dwordx4 v[68:71], v232, s[4:5] offset:1024
	global_load_dwordx4 v[72:75], v232, s[4:5] offset:2048
	global_load_dwordx4 v[76:79], v232, s[4:5] offset:3072
	s_add_u32 s4, s4, 0x1000
	s_addc_u32 s5, s5, 0
	global_load_dwordx4 v[80:83], v232, s[4:5]
	global_load_dwordx4 v[84:87], v232, s[4:5] offset:1024
	global_load_dwordx4 v[88:91], v232, s[4:5] offset:2048
	global_load_dwordx4 v[92:95], v232, s[4:5] offset:3072
	s_waitcnt vmcnt(26)
	v_pk_add_f32 v[204:205], v[32:33], v[34:35]
	v_pk_add_f32 v[206:207], v[36:37], v[38:39]
	v_pk_add_f32 v[208:209], v[40:41], v[42:43]
	v_pk_add_f32 v[210:211], v[44:45], v[46:47]
	v_pk_add_f32 v[216:217], v[48:49], v[50:51]
	v_pk_add_f32 v[218:219], v[52:53], v[54:55]
	v_pk_add_f32 v[220:221], v[56:57], v[58:59]
	v_pk_add_f32 v[222:223], v[60:61], v[62:63]
	v_pk_add_f32 v[204:205], v[204:205], v[206:207]
	v_pk_add_f32 v[208:209], v[208:209], v[210:211]
	v_pk_add_f32 v[216:217], v[216:217], v[218:219]
	v_pk_add_f32 v[220:221], v[220:221], v[222:223]
	v_pk_add_f32 v[204:205], v[204:205], v[208:209]
	v_pk_add_f32 v[216:217], v[216:217], v[220:221]
	v_add_f32_e32 v204, v204, v205
	v_add_f32_e32 v216, v216, v217
	s_nop 1
	v_add_f32_dpp v204, v204, v204 row_ror:1 row_mask:0xf bank_mask:0xf bound_ctrl:1
	v_add_f32_dpp v216, v216, v216 row_ror:1 row_mask:0xf bank_mask:0xf bound_ctrl:1
	s_nop 0
	v_add_f32_dpp v204, v204, v204 row_ror:2 row_mask:0xf bank_mask:0xf bound_ctrl:1
	v_add_f32_dpp v216, v216, v216 row_ror:2 row_mask:0xf bank_mask:0xf bound_ctrl:1
	s_nop 0
	v_add_f32_dpp v204, v204, v204 row_ror:4 row_mask:0xf bank_mask:0xf bound_ctrl:1
	v_add_f32_dpp v216, v216, v216 row_ror:4 row_mask:0xf bank_mask:0xf bound_ctrl:1
	s_nop 0
	v_add_f32_dpp v204, v204, v204 row_ror:8 row_mask:0xf bank_mask:0xf bound_ctrl:1
	v_add_f32_dpp v216, v216, v216 row_ror:8 row_mask:0xf bank_mask:0xf bound_ctrl:1
	s_nop 0
	v_mov_b32_e32 v205, v204
	v_mov_b32_e32 v217, v216
	s_nop 1
	v_permlane16_swap_b32_e32 v204, v205
	v_permlane16_swap_b32_e32 v216, v217
	s_nop 0
	v_add_f32_e32 v204, v204, v205
	v_add_f32_e32 v216, v216, v217
	v_mov_b32_e32 v205, v204
	v_mov_b32_e32 v217, v216
	s_nop 1
	v_permlane32_swap_b32_e32 v204, v205
	v_permlane32_swap_b32_e32 v216, v217
	s_nop 0
	v_add_f32_e32 v204, v204, v205
	v_add_f32_e32 v216, v216, v217
	v_mul_f32_e32 v212, 0x3a800000, v204
	v_mul_f32_e32 v224, 0x3a800000, v216
	v_pk_add_f32 v[32:33], v[32:33], v[212:213] op_sel_hi:[1,0] neg_lo:[0,1] neg_hi:[0,1]
	v_pk_add_f32 v[34:35], v[34:35], v[212:213] op_sel_hi:[1,0] neg_lo:[0,1] neg_hi:[0,1]
	v_pk_add_f32 v[36:37], v[36:37], v[212:213] op_sel_hi:[1,0] neg_lo:[0,1] neg_hi:[0,1]
	v_pk_add_f32 v[38:39], v[38:39], v[212:213] op_sel_hi:[1,0] neg_lo:[0,1] neg_hi:[0,1]
	v_pk_add_f32 v[40:41], v[40:41], v[212:213] op_sel_hi:[1,0] neg_lo:[0,1] neg_hi:[0,1]
	v_pk_add_f32 v[42:43], v[42:43], v[212:213] op_sel_hi:[1,0] neg_lo:[0,1] neg_hi:[0,1]
	v_pk_add_f32 v[44:45], v[44:45], v[212:213] op_sel_hi:[1,0] neg_lo:[0,1] neg_hi:[0,1]
	v_pk_add_f32 v[46:47], v[46:47], v[212:213] op_sel_hi:[1,0] neg_lo:[0,1] neg_hi:[0,1]
	v_pk_add_f32 v[48:49], v[48:49], v[224:225] op_sel_hi:[1,0] neg_lo:[0,1] neg_hi:[0,1]
	v_pk_add_f32 v[50:51], v[50:51], v[224:225] op_sel_hi:[1,0] neg_lo:[0,1] neg_hi:[0,1]
	v_pk_add_f32 v[52:53], v[52:53], v[224:225] op_sel_hi:[1,0] neg_lo:[0,1] neg_hi:[0,1]
	v_pk_add_f32 v[54:55], v[54:55], v[224:225] op_sel_hi:[1,0] neg_lo:[0,1] neg_hi:[0,1]
	v_pk_add_f32 v[56:57], v[56:57], v[224:225] op_sel_hi:[1,0] neg_lo:[0,1] neg_hi:[0,1]
	v_pk_add_f32 v[58:59], v[58:59], v[224:225] op_sel_hi:[1,0] neg_lo:[0,1] neg_hi:[0,1]
	v_pk_add_f32 v[60:61], v[60:61], v[224:225] op_sel_hi:[1,0] neg_lo:[0,1] neg_hi:[0,1]
	v_pk_add_f32 v[62:63], v[62:63], v[224:225] op_sel_hi:[1,0] neg_lo:[0,1] neg_hi:[0,1]
	v_pk_mul_f32 v[204:205], v[32:33], v[32:33]
	v_pk_mul_f32 v[206:207], v[34:35], v[34:35]
	v_pk_mul_f32 v[216:217], v[48:49], v[48:49]
	v_pk_mul_f32 v[218:219], v[50:51], v[50:51]
	v_pk_fma_f32 v[204:205], v[36:37], v[36:37], v[204:205]
	v_pk_fma_f32 v[206:207], v[38:39], v[38:39], v[206:207]
	v_pk_fma_f32 v[216:217], v[52:53], v[52:53], v[216:217]
	v_pk_fma_f32 v[218:219], v[54:55], v[54:55], v[218:219]
	v_pk_fma_f32 v[204:205], v[40:41], v[40:41], v[204:205]
	v_pk_fma_f32 v[206:207], v[42:43], v[42:43], v[206:207]
	v_pk_fma_f32 v[216:217], v[56:57], v[56:57], v[216:217]
	v_pk_fma_f32 v[218:219], v[58:59], v[58:59], v[218:219]
	v_pk_fma_f32 v[204:205], v[44:45], v[44:45], v[204:205]
	v_pk_fma_f32 v[206:207], v[46:47], v[46:47], v[206:207]
	v_pk_fma_f32 v[216:217], v[60:61], v[60:61], v[216:217]
	v_pk_fma_f32 v[218:219], v[62:63], v[62:63], v[218:219]
	v_pk_add_f32 v[204:205], v[204:205], v[206:207]
	v_pk_add_f32 v[216:217], v[216:217], v[218:219]
	v_add_f32_e32 v204, v204, v205
	v_add_f32_e32 v216, v216, v217
	s_nop 1
	v_add_f32_dpp v204, v204, v204 row_ror:1 row_mask:0xf bank_mask:0xf bound_ctrl:1
	v_add_f32_dpp v216, v216, v216 row_ror:1 row_mask:0xf bank_mask:0xf bound_ctrl:1
	s_nop 0
	v_add_f32_dpp v204, v204, v204 row_ror:2 row_mask:0xf bank_mask:0xf bound_ctrl:1
	v_add_f32_dpp v216, v216, v216 row_ror:2 row_mask:0xf bank_mask:0xf bound_ctrl:1
	s_nop 0
	v_add_f32_dpp v204, v204, v204 row_ror:4 row_mask:0xf bank_mask:0xf bound_ctrl:1
	v_add_f32_dpp v216, v216, v216 row_ror:4 row_mask:0xf bank_mask:0xf bound_ctrl:1
	s_nop 0
	v_add_f32_dpp v204, v204, v204 row_ror:8 row_mask:0xf bank_mask:0xf bound_ctrl:1
	v_add_f32_dpp v216, v216, v216 row_ror:8 row_mask:0xf bank_mask:0xf bound_ctrl:1
	s_nop 0
	v_mov_b32_e32 v205, v204
	v_mov_b32_e32 v217, v216
	s_nop 1
	v_permlane16_swap_b32_e32 v204, v205
	v_permlane16_swap_b32_e32 v216, v217
	s_nop 0
	v_add_f32_e32 v204, v204, v205
	v_add_f32_e32 v216, v216, v217
	v_mov_b32_e32 v205, v204
	v_mov_b32_e32 v217, v216
	s_nop 1
	v_permlane32_swap_b32_e32 v204, v205
	v_permlane32_swap_b32_e32 v216, v217
	s_nop 0
	v_add_f32_e32 v204, v204, v205
	v_add_f32_e32 v216, v216, v217
	v_mov_b32_e32 v205, 0x3727c5ac
	v_fmac_f32_e32 v205, 0x3a800000, v204
	v_mov_b32_e32 v217, 0x3727c5ac
	v_fmac_f32_e32 v217, 0x3a800000, v216
	v_mul_f32_e32 v206, 0x4b800000, v205
	s_mov_b32 s4, 0x800000
	v_cmp_gt_f32_e32 vcc, s4, v205
	s_nop 1
	v_cndmask_b32_e32 v205, v205, v206, vcc
	v_rsq_f32_e32 v205, v205
	s_nop 0
	v_mul_f32_e32 v206, 0x45800000, v205
	v_cndmask_b32_e32 v214, v205, v206, vcc
	v_mul_f32_e32 v218, 0x4b800000, v217
	s_mov_b32 s4, 0x800000
	v_cmp_gt_f32_e32 vcc, s4, v217
	s_nop 1
	v_cndmask_b32_e32 v217, v217, v218, vcc
	v_rsq_f32_e32 v217, v217
	s_nop 0
	v_mul_f32_e32 v218, 0x45800000, v217
	v_cndmask_b32_e32 v226, v217, v218, vcc
	v_pk_mul_f32 v[32:33], v[32:33], v[214:215] op_sel_hi:[1,0]
	v_pk_mul_f32 v[34:35], v[34:35], v[214:215] op_sel_hi:[1,0]
	v_pk_mul_f32 v[36:37], v[36:37], v[214:215] op_sel_hi:[1,0]
	v_pk_mul_f32 v[38:39], v[38:39], v[214:215] op_sel_hi:[1,0]
	v_pk_mul_f32 v[40:41], v[40:41], v[214:215] op_sel_hi:[1,0]
	v_pk_mul_f32 v[42:43], v[42:43], v[214:215] op_sel_hi:[1,0]
	v_pk_mul_f32 v[44:45], v[44:45], v[214:215] op_sel_hi:[1,0]
	v_pk_mul_f32 v[46:47], v[46:47], v[214:215] op_sel_hi:[1,0]
	v_pk_mul_f32 v[48:49], v[48:49], v[226:227] op_sel_hi:[1,0]
	v_pk_mul_f32 v[50:51], v[50:51], v[226:227] op_sel_hi:[1,0]
	v_pk_mul_f32 v[52:53], v[52:53], v[226:227] op_sel_hi:[1,0]
	v_pk_mul_f32 v[54:55], v[54:55], v[226:227] op_sel_hi:[1,0]
	v_pk_mul_f32 v[56:57], v[56:57], v[226:227] op_sel_hi:[1,0]
	v_pk_mul_f32 v[58:59], v[58:59], v[226:227] op_sel_hi:[1,0]
	v_pk_mul_f32 v[60:61], v[60:61], v[226:227] op_sel_hi:[1,0]
	v_pk_mul_f32 v[62:63], v[62:63], v[226:227] op_sel_hi:[1,0]
	v_pk_fma_f32 v[32:33], v[136:137], v[32:33], v[152:153]
	v_pk_fma_f32 v[34:35], v[138:139], v[34:35], v[154:155]
	v_pk_fma_f32 v[36:37], v[140:141], v[36:37], v[156:157]
	v_pk_fma_f32 v[38:39], v[142:143], v[38:39], v[158:159]
	v_pk_fma_f32 v[40:41], v[144:145], v[40:41], v[160:161]
	v_pk_fma_f32 v[42:43], v[146:147], v[42:43], v[162:163]
	v_pk_fma_f32 v[44:45], v[148:149], v[44:45], v[164:165]
	v_pk_fma_f32 v[46:47], v[150:151], v[46:47], v[166:167]
	v_pk_fma_f32 v[48:49], v[136:137], v[48:49], v[152:153]
	v_pk_fma_f32 v[50:51], v[138:139], v[50:51], v[154:155]
	v_pk_fma_f32 v[52:53], v[140:141], v[52:53], v[156:157]
	v_pk_fma_f32 v[54:55], v[142:143], v[54:55], v[158:159]
	v_pk_fma_f32 v[56:57], v[144:145], v[56:57], v[160:161]
	v_pk_fma_f32 v[58:59], v[146:147], v[58:59], v[162:163]
	v_pk_fma_f32 v[60:61], v[148:149], v[60:61], v[164:165]
	v_pk_fma_f32 v[62:63], v[150:151], v[62:63], v[166:167]
	v_mov_b32_e32 v228, v212
	v_mov_b32_e32 v229, v214
	v_mov_b32_e32 v168, v224
	v_mov_b32_e32 v169, v226
	v_add_f32_e32 v112, 1.0, v112
	v_add_f32_e32 v113, 1.0, v113
	v_add_f32_e32 v114, 1.0, v114
	v_add_f32_e32 v115, 1.0, v115
	v_add_f32_e32 v116, 1.0, v116
	v_add_f32_e32 v117, 1.0, v117
	v_add_f32_e32 v118, 1.0, v118
	v_add_f32_e32 v119, 1.0, v119
	v_add_f32_e32 v120, 1.0, v120
	v_add_f32_e32 v121, 1.0, v121
	v_add_f32_e32 v122, 1.0, v122
	v_add_f32_e32 v123, 1.0, v123
	v_add_f32_e32 v124, 1.0, v124
	v_add_f32_e32 v125, 1.0, v125
	v_add_f32_e32 v126, 1.0, v126
	v_add_f32_e32 v127, 1.0, v127
	v_pk_fma_f32 v[204:205], v[112:113], v[32:33], v[96:97]
	v_pk_fma_f32 v[206:207], v[114:115], v[34:35], v[98:99]
	v_pk_fma_f32 v[208:209], v[116:117], v[36:37], v[100:101]
	v_pk_fma_f32 v[210:211], v[118:119], v[38:39], v[102:103]
	v_pk_fma_f32 v[212:213], v[120:121], v[40:41], v[104:105]
	v_pk_fma_f32 v[214:215], v[122:123], v[42:43], v[106:107]
	v_pk_fma_f32 v[216:217], v[124:125], v[44:45], v[108:109]
	v_pk_fma_f32 v[218:219], v[126:127], v[46:47], v[110:111]
	v_cvt_pk_bf16_f32 v220, v204, v205
	v_cvt_pk_bf16_f32 v221, v206, v207
	v_cvt_pk_bf16_f32 v222, v208, v209
	v_cvt_pk_bf16_f32 v223, v210, v211
	v_cvt_pk_bf16_f32 v224, v212, v213
	v_cvt_pk_bf16_f32 v225, v214, v215
	v_cvt_pk_bf16_f32 v226, v216, v217
	v_cvt_pk_bf16_f32 v227, v218, v219
	s_mul_i32 s4, s6, 0x880
	s_add_u32 s4, s4, 0xe9e6000
	s_add_u32 s4, s4, s8
	s_addc_u32 s5, s9, 0
	global_store_dwordx2 v233, v[220:221], s[4:5]
	global_store_dwordx2 v233, v[222:223], s[4:5] offset:512
	global_store_dwordx2 v233, v[224:225], s[4:5] offset:1024
	global_store_dwordx2 v233, v[226:227], s[4:5] offset:1536
	s_mov_b64 s[12:13], exec
	s_mov_b64 exec, 1
	global_store_dwordx2 v129, v[228:229], s[4:5] offset:2048
	s_mov_b64 exec, s[12:13]
	v_pk_fma_f32 v[204:205], v[112:113], v[48:49], v[96:97]
	v_pk_fma_f32 v[206:207], v[114:115], v[50:51], v[98:99]
	v_pk_fma_f32 v[208:209], v[116:117], v[52:53], v[100:101]
	v_pk_fma_f32 v[210:211], v[118:119], v[54:55], v[102:103]
	v_pk_fma_f32 v[212:213], v[120:121], v[56:57], v[104:105]
	v_pk_fma_f32 v[214:215], v[122:123], v[58:59], v[106:107]
	v_pk_fma_f32 v[216:217], v[124:125], v[60:61], v[108:109]
	v_pk_fma_f32 v[218:219], v[126:127], v[62:63], v[110:111]
	v_cvt_pk_bf16_f32 v220, v204, v205
	v_cvt_pk_bf16_f32 v221, v206, v207
	v_cvt_pk_bf16_f32 v222, v208, v209
	v_cvt_pk_bf16_f32 v223, v210, v211
	v_cvt_pk_bf16_f32 v224, v212, v213
	v_cvt_pk_bf16_f32 v225, v214, v215
	v_cvt_pk_bf16_f32 v226, v216, v217
	v_cvt_pk_bf16_f32 v227, v218, v219
	s_mul_i32 s4, s6, 0x880
	s_add_u32 s4, s4, 0xee26000
	s_add_u32 s4, s4, s8
	s_addc_u32 s5, s9, 0
	global_store_dwordx2 v233, v[220:221], s[4:5]
	global_store_dwordx2 v233, v[222:223], s[4:5] offset:512
	global_store_dwordx2 v233, v[224:225], s[4:5] offset:1024
	global_store_dwordx2 v233, v[226:227], s[4:5] offset:1536
	s_mov_b64 s[12:13], exec
	s_mov_b64 exec, 1
	global_store_dwordx2 v129, v[168:169], s[4:5] offset:2048
	s_mov_b64 exec, s[12:13]
	s_waitcnt vmcnt(10)
	v_pk_add_f32 v[204:205], v[0:1], v[2:3]
	v_pk_add_f32 v[206:207], v[4:5], v[6:7]
	v_pk_add_f32 v[208:209], v[8:9], v[10:11]
	v_pk_add_f32 v[210:211], v[12:13], v[14:15]
	v_pk_add_f32 v[216:217], v[16:17], v[18:19]
	v_pk_add_f32 v[218:219], v[20:21], v[22:23]
	v_pk_add_f32 v[220:221], v[24:25], v[26:27]
	v_pk_add_f32 v[222:223], v[28:29], v[30:31]
	v_pk_add_f32 v[204:205], v[204:205], v[206:207]
	v_pk_add_f32 v[208:209], v[208:209], v[210:211]
	v_pk_add_f32 v[216:217], v[216:217], v[218:219]
	v_pk_add_f32 v[220:221], v[220:221], v[222:223]
	v_pk_add_f32 v[204:205], v[204:205], v[208:209]
	v_pk_add_f32 v[216:217], v[216:217], v[220:221]
	v_add_f32_e32 v204, v204, v205
	v_add_f32_e32 v216, v216, v217
	s_nop 1
	v_add_f32_dpp v204, v204, v204 row_ror:1 row_mask:0xf bank_mask:0xf bound_ctrl:1
	v_add_f32_dpp v216, v216, v216 row_ror:1 row_mask:0xf bank_mask:0xf bound_ctrl:1
	s_nop 0
	v_add_f32_dpp v204, v204, v204 row_ror:2 row_mask:0xf bank_mask:0xf bound_ctrl:1
	v_add_f32_dpp v216, v216, v216 row_ror:2 row_mask:0xf bank_mask:0xf bound_ctrl:1
	s_nop 0
	v_add_f32_dpp v204, v204, v204 row_ror:4 row_mask:0xf bank_mask:0xf bound_ctrl:1
	v_add_f32_dpp v216, v216, v216 row_ror:4 row_mask:0xf bank_mask:0xf bound_ctrl:1
	s_nop 0
	v_add_f32_dpp v204, v204, v204 row_ror:8 row_mask:0xf bank_mask:0xf bound_ctrl:1
	v_add_f32_dpp v216, v216, v216 row_ror:8 row_mask:0xf bank_mask:0xf bound_ctrl:1
	s_nop 0
	v_mov_b32_e32 v205, v204
	v_mov_b32_e32 v217, v216
	s_nop 1
	v_permlane16_swap_b32_e32 v204, v205
	v_permlane16_swap_b32_e32 v216, v217
	s_nop 0
	v_add_f32_e32 v204, v204, v205
	v_add_f32_e32 v216, v216, v217
	v_mov_b32_e32 v205, v204
	v_mov_b32_e32 v217, v216
	s_nop 1
	v_permlane32_swap_b32_e32 v204, v205
	v_permlane32_swap_b32_e32 v216, v217
	s_nop 0
	v_add_f32_e32 v204, v204, v205
	v_add_f32_e32 v216, v216, v217
	v_mul_f32_e32 v212, 0x3a800000, v204
	v_mul_f32_e32 v224, 0x3a800000, v216
	v_pk_add_f32 v[0:1], v[0:1], v[212:213] op_sel_hi:[1,0] neg_lo:[0,1] neg_hi:[0,1]
	v_pk_add_f32 v[2:3], v[2:3], v[212:213] op_sel_hi:[1,0] neg_lo:[0,1] neg_hi:[0,1]
	v_pk_add_f32 v[4:5], v[4:5], v[212:213] op_sel_hi:[1,0] neg_lo:[0,1] neg_hi:[0,1]
	v_pk_add_f32 v[6:7], v[6:7], v[212:213] op_sel_hi:[1,0] neg_lo:[0,1] neg_hi:[0,1]
	v_pk_add_f32 v[8:9], v[8:9], v[212:213] op_sel_hi:[1,0] neg_lo:[0,1] neg_hi:[0,1]
	v_pk_add_f32 v[10:11], v[10:11], v[212:213] op_sel_hi:[1,0] neg_lo:[0,1] neg_hi:[0,1]
	v_pk_add_f32 v[12:13], v[12:13], v[212:213] op_sel_hi:[1,0] neg_lo:[0,1] neg_hi:[0,1]
	v_pk_add_f32 v[14:15], v[14:15], v[212:213] op_sel_hi:[1,0] neg_lo:[0,1] neg_hi:[0,1]
	v_pk_add_f32 v[16:17], v[16:17], v[224:225] op_sel_hi:[1,0] neg_lo:[0,1] neg_hi:[0,1]
	v_pk_add_f32 v[18:19], v[18:19], v[224:225] op_sel_hi:[1,0] neg_lo:[0,1] neg_hi:[0,1]
	v_pk_add_f32 v[20:21], v[20:21], v[224:225] op_sel_hi:[1,0] neg_lo:[0,1] neg_hi:[0,1]
	v_pk_add_f32 v[22:23], v[22:23], v[224:225] op_sel_hi:[1,0] neg_lo:[0,1] neg_hi:[0,1]
	v_pk_add_f32 v[24:25], v[24:25], v[224:225] op_sel_hi:[1,0] neg_lo:[0,1] neg_hi:[0,1]
	v_pk_add_f32 v[26:27], v[26:27], v[224:225] op_sel_hi:[1,0] neg_lo:[0,1] neg_hi:[0,1]
	v_pk_add_f32 v[28:29], v[28:29], v[224:225] op_sel_hi:[1,0] neg_lo:[0,1] neg_hi:[0,1]
	v_pk_add_f32 v[30:31], v[30:31], v[224:225] op_sel_hi:[1,0] neg_lo:[0,1] neg_hi:[0,1]
	v_pk_mul_f32 v[204:205], v[0:1], v[0:1]
	v_pk_mul_f32 v[206:207], v[2:3], v[2:3]
	v_pk_mul_f32 v[216:217], v[16:17], v[16:17]
	v_pk_mul_f32 v[218:219], v[18:19], v[18:19]
	v_pk_fma_f32 v[204:205], v[4:5], v[4:5], v[204:205]
	v_pk_fma_f32 v[206:207], v[6:7], v[6:7], v[206:207]
	v_pk_fma_f32 v[216:217], v[20:21], v[20:21], v[216:217]
	v_pk_fma_f32 v[218:219], v[22:23], v[22:23], v[218:219]
	v_pk_fma_f32 v[204:205], v[8:9], v[8:9], v[204:205]
	v_pk_fma_f32 v[206:207], v[10:11], v[10:11], v[206:207]
	v_pk_fma_f32 v[216:217], v[24:25], v[24:25], v[216:217]
	v_pk_fma_f32 v[218:219], v[26:27], v[26:27], v[218:219]
	v_pk_fma_f32 v[204:205], v[12:13], v[12:13], v[204:205]
	v_pk_fma_f32 v[206:207], v[14:15], v[14:15], v[206:207]
	v_pk_fma_f32 v[216:217], v[28:29], v[28:29], v[216:217]
	v_pk_fma_f32 v[218:219], v[30:31], v[30:31], v[218:219]
	v_pk_add_f32 v[204:205], v[204:205], v[206:207]
	v_pk_add_f32 v[216:217], v[216:217], v[218:219]
	v_add_f32_e32 v204, v204, v205
	v_add_f32_e32 v216, v216, v217
	s_nop 1
	v_add_f32_dpp v204, v204, v204 row_ror:1 row_mask:0xf bank_mask:0xf bound_ctrl:1
	v_add_f32_dpp v216, v216, v216 row_ror:1 row_mask:0xf bank_mask:0xf bound_ctrl:1
	s_nop 0
	v_add_f32_dpp v204, v204, v204 row_ror:2 row_mask:0xf bank_mask:0xf bound_ctrl:1
	v_add_f32_dpp v216, v216, v216 row_ror:2 row_mask:0xf bank_mask:0xf bound_ctrl:1
	s_nop 0
	v_add_f32_dpp v204, v204, v204 row_ror:4 row_mask:0xf bank_mask:0xf bound_ctrl:1
	v_add_f32_dpp v216, v216, v216 row_ror:4 row_mask:0xf bank_mask:0xf bound_ctrl:1
	s_nop 0
	v_add_f32_dpp v204, v204, v204 row_ror:8 row_mask:0xf bank_mask:0xf bound_ctrl:1
	v_add_f32_dpp v216, v216, v216 row_ror:8 row_mask:0xf bank_mask:0xf bound_ctrl:1
	s_nop 0
	v_mov_b32_e32 v205, v204
	v_mov_b32_e32 v217, v216
	s_nop 1
	v_permlane16_swap_b32_e32 v204, v205
	v_permlane16_swap_b32_e32 v216, v217
	s_nop 0
	v_add_f32_e32 v204, v204, v205
	v_add_f32_e32 v216, v216, v217
	v_mov_b32_e32 v205, v204
	v_mov_b32_e32 v217, v216
	s_nop 1
	v_permlane32_swap_b32_e32 v204, v205
	v_permlane32_swap_b32_e32 v216, v217
	s_nop 0
	v_add_f32_e32 v204, v204, v205
	v_add_f32_e32 v216, v216, v217
	v_mov_b32_e32 v205, 0x3727c5ac
	v_fmac_f32_e32 v205, 0x3a800000, v204
	v_mov_b32_e32 v217, 0x3727c5ac
	v_fmac_f32_e32 v217, 0x3a800000, v216
	v_mul_f32_e32 v206, 0x4b800000, v205
	s_mov_b32 s4, 0x800000
	v_cmp_gt_f32_e32 vcc, s4, v205
	s_nop 1
	v_cndmask_b32_e32 v205, v205, v206, vcc
	v_rsq_f32_e32 v205, v205
	s_nop 0
	v_mul_f32_e32 v206, 0x45800000, v205
	v_cndmask_b32_e32 v214, v205, v206, vcc
	v_mul_f32_e32 v218, 0x4b800000, v217
	s_mov_b32 s4, 0x800000
	v_cmp_gt_f32_e32 vcc, s4, v217
	s_nop 1
	v_cndmask_b32_e32 v217, v217, v218, vcc
	v_rsq_f32_e32 v217, v217
	s_nop 0
	v_mul_f32_e32 v218, 0x45800000, v217
	v_cndmask_b32_e32 v226, v217, v218, vcc
	v_pk_mul_f32 v[0:1], v[0:1], v[214:215] op_sel_hi:[1,0]
	v_pk_mul_f32 v[2:3], v[2:3], v[214:215] op_sel_hi:[1,0]
	v_pk_mul_f32 v[4:5], v[4:5], v[214:215] op_sel_hi:[1,0]
	v_pk_mul_f32 v[6:7], v[6:7], v[214:215] op_sel_hi:[1,0]
	v_pk_mul_f32 v[8:9], v[8:9], v[214:215] op_sel_hi:[1,0]
	v_pk_mul_f32 v[10:11], v[10:11], v[214:215] op_sel_hi:[1,0]
	v_pk_mul_f32 v[12:13], v[12:13], v[214:215] op_sel_hi:[1,0]
	v_pk_mul_f32 v[14:15], v[14:15], v[214:215] op_sel_hi:[1,0]
	v_pk_mul_f32 v[16:17], v[16:17], v[226:227] op_sel_hi:[1,0]
	v_pk_mul_f32 v[18:19], v[18:19], v[226:227] op_sel_hi:[1,0]
	v_pk_mul_f32 v[20:21], v[20:21], v[226:227] op_sel_hi:[1,0]
	v_pk_mul_f32 v[22:23], v[22:23], v[226:227] op_sel_hi:[1,0]
	v_pk_mul_f32 v[24:25], v[24:25], v[226:227] op_sel_hi:[1,0]
	v_pk_mul_f32 v[26:27], v[26:27], v[226:227] op_sel_hi:[1,0]
	v_pk_mul_f32 v[28:29], v[28:29], v[226:227] op_sel_hi:[1,0]
	v_pk_mul_f32 v[30:31], v[30:31], v[226:227] op_sel_hi:[1,0]
	v_pk_fma_f32 v[0:1], v[136:137], v[0:1], v[152:153]
	v_pk_fma_f32 v[2:3], v[138:139], v[2:3], v[154:155]
	v_pk_fma_f32 v[4:5], v[140:141], v[4:5], v[156:157]
	v_pk_fma_f32 v[6:7], v[142:143], v[6:7], v[158:159]
	v_pk_fma_f32 v[8:9], v[144:145], v[8:9], v[160:161]
	v_pk_fma_f32 v[10:11], v[146:147], v[10:11], v[162:163]
	v_pk_fma_f32 v[12:13], v[148:149], v[12:13], v[164:165]
	v_pk_fma_f32 v[14:15], v[150:151], v[14:15], v[166:167]
	v_pk_fma_f32 v[16:17], v[136:137], v[16:17], v[152:153]
	v_pk_fma_f32 v[18:19], v[138:139], v[18:19], v[154:155]
	v_pk_fma_f32 v[20:21], v[140:141], v[20:21], v[156:157]
	v_pk_fma_f32 v[22:23], v[142:143], v[22:23], v[158:159]
	v_pk_fma_f32 v[24:25], v[144:145], v[24:25], v[160:161]
	v_pk_fma_f32 v[26:27], v[146:147], v[26:27], v[162:163]
	v_pk_fma_f32 v[28:29], v[148:149], v[28:29], v[164:165]
	v_pk_fma_f32 v[30:31], v[150:151], v[30:31], v[166:167]
	v_mov_b32_e32 v228, v212
	v_mov_b32_e32 v229, v214
	v_mov_b32_e32 v168, v224
	v_mov_b32_e32 v169, v226
	v_add_f32_e32 v80, 1.0, v80
	v_add_f32_e32 v81, 1.0, v81
	v_add_f32_e32 v82, 1.0, v82
	v_add_f32_e32 v83, 1.0, v83
	v_add_f32_e32 v84, 1.0, v84
	v_add_f32_e32 v85, 1.0, v85
	v_add_f32_e32 v86, 1.0, v86
	v_add_f32_e32 v87, 1.0, v87
	v_add_f32_e32 v88, 1.0, v88
	v_add_f32_e32 v89, 1.0, v89
	v_add_f32_e32 v90, 1.0, v90
	v_add_f32_e32 v91, 1.0, v91
	v_add_f32_e32 v92, 1.0, v92
	v_add_f32_e32 v93, 1.0, v93
	v_add_f32_e32 v94, 1.0, v94
	v_add_f32_e32 v95, 1.0, v95
	v_pk_fma_f32 v[204:205], v[80:81], v[0:1], v[64:65]
	v_pk_fma_f32 v[206:207], v[82:83], v[2:3], v[66:67]
	v_pk_fma_f32 v[208:209], v[84:85], v[4:5], v[68:69]
	v_pk_fma_f32 v[210:211], v[86:87], v[6:7], v[70:71]
	v_pk_fma_f32 v[212:213], v[88:89], v[8:9], v[72:73]
	v_pk_fma_f32 v[214:215], v[90:91], v[10:11], v[74:75]
	v_pk_fma_f32 v[216:217], v[92:93], v[12:13], v[76:77]
	v_pk_fma_f32 v[218:219], v[94:95], v[14:15], v[78:79]
	v_cvt_pk_bf16_f32 v220, v204, v205
	v_cvt_pk_bf16_f32 v221, v206, v207
	v_cvt_pk_bf16_f32 v222, v208, v209
	v_cvt_pk_bf16_f32 v223, v210, v211
	v_cvt_pk_bf16_f32 v224, v212, v213
	v_cvt_pk_bf16_f32 v225, v214, v215
	v_cvt_pk_bf16_f32 v226, v216, v217
	v_cvt_pk_bf16_f32 v227, v218, v219
	s_mul_i32 s4, s6, 0x880
	s_add_u32 s4, s4, 0xf266000
	s_add_u32 s4, s4, s8
	s_addc_u32 s5, s9, 0
	global_store_dwordx2 v233, v[220:221], s[4:5]
	global_store_dwordx2 v233, v[222:223], s[4:5] offset:512
	global_store_dwordx2 v233, v[224:225], s[4:5] offset:1024
	global_store_dwordx2 v233, v[226:227], s[4:5] offset:1536
	s_mov_b64 s[12:13], exec
	s_mov_b64 exec, 1
	global_store_dwordx2 v129, v[228:229], s[4:5] offset:2048
	s_mov_b64 exec, s[12:13]
	v_pk_fma_f32 v[204:205], v[80:81], v[16:17], v[64:65]
	v_pk_fma_f32 v[206:207], v[82:83], v[18:19], v[66:67]
	v_pk_fma_f32 v[208:209], v[84:85], v[20:21], v[68:69]
	v_pk_fma_f32 v[210:211], v[86:87], v[22:23], v[70:71]
	v_pk_fma_f32 v[212:213], v[88:89], v[24:25], v[72:73]
	v_pk_fma_f32 v[214:215], v[90:91], v[26:27], v[74:75]
	v_pk_fma_f32 v[216:217], v[92:93], v[28:29], v[76:77]
	v_pk_fma_f32 v[218:219], v[94:95], v[30:31], v[78:79]
	v_cvt_pk_bf16_f32 v220, v204, v205
	v_cvt_pk_bf16_f32 v221, v206, v207
	v_cvt_pk_bf16_f32 v222, v208, v209
	v_cvt_pk_bf16_f32 v223, v210, v211
	v_cvt_pk_bf16_f32 v224, v212, v213
	v_cvt_pk_bf16_f32 v225, v214, v215
	v_cvt_pk_bf16_f32 v226, v216, v217
	v_cvt_pk_bf16_f32 v227, v218, v219
	s_mul_i32 s4, s6, 0x880
	s_add_u32 s4, s4, 0xf6a6000
	s_add_u32 s4, s4, s8
	s_addc_u32 s5, s9, 0
	global_store_dwordx2 v233, v[220:221], s[4:5]
	global_store_dwordx2 v233, v[222:223], s[4:5] offset:512
	global_store_dwordx2 v233, v[224:225], s[4:5] offset:1024
	global_store_dwordx2 v233, v[226:227], s[4:5] offset:1536
	s_mov_b64 s[12:13], exec
	s_mov_b64 exec, 1
	global_store_dwordx2 v129, v[168:169], s[4:5] offset:2048
	s_mov_b64 exec, s[12:13]
	s_waitcnt vmcnt(0)
	s_branch .LBB0_103

.LBB0_1198:
	s_andn2_b64 vcc, exec, s[34:35]
	s_mov_b64 s[40:41], 0
	v_readlane_b32 s2, v235, 48
	s_cbranch_vccnz .LBB0_1212
	v_readlane_b32 s4, v235, 51
	s_cmp_gt_i32 s2, 0
	s_mov_b64 s[40:41], -1
	v_readlane_b32 s5, v235, 52
	s_cbranch_scc0 .LBB0_1213
	s_cmp_gt_i32 s2, 1
	s_mov_b64 s[4:5], -1
	s_cbranch_scc0 .LBB0_1419
	s_waitcnt lgkmcnt(0)
	v_mov_b32_e32 v34, v170
	v_mov_b32_e32 v0, v170
	v_readlane_b32 s4, v235, 17
	v_ashrrev_i32_e32 v33, 6, v0
	s_nop 0
	v_add_u32_e32 v32, s4, v33
	s_movk_i32 s4, 0x3000
	v_cmp_gt_i32_e32 vcc, s4, v32
	s_and_saveexec_b64 s[36:37], vcc
	s_cbranch_execz .LBB0_1420
	v_readlane_b32 s4, v235, 33
	s_cmp_lg_u32 s4, 0x200
	s_cbranch_scc1 .Llnc_orig
	v_and_b32_e32 v232, 63, v170
	v_lshlrev_b32_e32 v233, 3, v232
	v_lshlrev_b32_e32 v232, 4, v232
	v_lshrrev_b32_e32 v231, 6, v170
	s_nop 0
	v_readfirstlane_b32 s6, v231
	v_readlane_b32 s7, v237, 0
	s_lshl_b32 s7, s7, 2
	s_add_u32 s6, s6, s7
	v_readlane_b32 s8, v235, 34
	v_readlane_b32 s9, v235, 35
	v_readlane_b32 s7, v235, 44
	s_mul_i32 s10, s7, 3
	s_add_u32 s10, s10, 0
	s_lshl_b32 s10, s10, 12
	v_readlane_b32 s4, v237, 25
	v_readlane_b32 s5, v237, 26
	s_add_u32 s4, s4, s10
	s_addc_u32 s5, s5, 0
	global_load_dwordx4 v[136:139], v232, s[4:5]
	global_load_dwordx4 v[140:143], v232, s[4:5] offset:1024
	global_load_dwordx4 v[144:147], v232, s[4:5] offset:2048
	global_load_dwordx4 v[148:151], v232, s[4:5] offset:3072
	v_readlane_b32 s4, v237, 27
	v_readlane_b32 s5, v237, 28
	s_add_u32 s4, s4, s10
	s_addc_u32 s5, s5, 0
	global_load_dwordx4 v[152:155], v232, s[4:5]
	global_load_dwordx4 v[156:159], v232, s[4:5] offset:1024
	global_load_dwordx4 v[160:163], v232, s[4:5] offset:2048
	global_load_dwordx4 v[164:167], v232, s[4:5] offset:3072
	s_mov_b32 s11, s7
	s_mul_i32 s11, s11, 0x1b000
	s_add_u32 s11, s11, 0xb0fb000
	s_add_u32 s10, s8, s11
	s_addc_u32 s11, s9, 0
	s_add_u32 s4, s10, 0x0
	s_addc_u32 s5, s11, 0
	global_load_dwordx4 v[64:67], v232, s[4:5]
	global_load_dwordx4 v[68:71], v232, s[4:5] offset:1024
	global_load_dwordx4 v[72:75], v232, s[4:5] offset:2048
	global_load_dwordx4 v[76:79], v232, s[4:5] offset:3072
	s_add_u32 s4, s4, 0x1000
	s_addc_u32 s5, s5, 0
	global_load_dwordx4 v[80:83], v232, s[4:5]
	global_load_dwordx4 v[84:87], v232, s[4:5] offset:1024
	global_load_dwordx4 v[88:91], v232, s[4:5] offset:2048
	global_load_dwordx4 v[92:95], v232, s[4:5] offset:3072
	s_lshl_b32 s4, s6, 12
	s_add_u32 s4, s4, 0xb166000
	s_add_u32 s4, s4, s8
	s_addc_u32 s5, s9, 0
	global_load_dwordx4 v[0:3], v232, s[4:5]
	global_load_dwordx4 v[4:7], v232, s[4:5] offset:1024
	global_load_dwordx4 v[8:11], v232, s[4:5] offset:2048
	global_load_dwordx4 v[12:15], v232, s[4:5] offset:3072
	s_lshl_b32 s4, s6, 12
	s_add_u32 s4, s4, 0xb966000
	s_add_u32 s4, s4, s8
	s_addc_u32 s5, s9, 0
	global_load_dwordx4 v[16:19], v232, s[4:5]
	global_load_dwordx4 v[20:23], v232, s[4:5] offset:1024
	global_load_dwordx4 v[24:27], v232, s[4:5] offset:2048
	global_load_dwordx4 v[28:31], v232, s[4:5] offset:3072
	s_waitcnt vmcnt(0)
	s_lshl_b32 s4, s6, 12
	s_add_u32 s4, s4, 0xc166000
	s_add_u32 s4, s4, s8
	s_addc_u32 s5, s9, 0
	global_load_dwordx4 v[32:35], v232, s[4:5]
	global_load_dwordx4 v[36:39], v232, s[4:5] offset:1024
	global_load_dwordx4 v[40:43], v232, s[4:5] offset:2048
	global_load_dwordx4 v[44:47], v232, s[4:5] offset:3072
	s_lshl_b32 s4, s6, 12
	s_add_u32 s4, s4, 0xc966000
	s_add_u32 s4, s4, s8
	s_addc_u32 s5, s9, 0
	global_load_dwordx4 v[48:51], v232, s[4:5]
	global_load_dwordx4 v[52:55], v232, s[4:5] offset:1024
	global_load_dwordx4 v[56:59], v232, s[4:5] offset:2048
	global_load_dwordx4 v[60:63], v232, s[4:5] offset:3072
	s_add_u32 s4, s10, 0x9000
	s_addc_u32 s5, s11, 0
	global_load_dwordx4 v[96:99], v232, s[4:5]
	global_load_dwordx4 v[100:103], v232, s[4:5] offset:1024
	global_load_dwordx4 v[104:107], v232, s[4:5] offset:2048
	global_load_dwordx4 v[108:111], v232, s[4:5] offset:3072
	s_add_u32 s4, s4, 0x1000
	s_addc_u32 s5, s5, 0
	global_load_dwordx4 v[112:115], v232, s[4:5]
	global_load_dwordx4 v[116:119], v232, s[4:5] offset:1024
	global_load_dwordx4 v[120:123], v232, s[4:5] offset:2048
	global_load_dwordx4 v[124:127], v232, s[4:5] offset:3072
	v_pk_add_f32 v[204:205], v[0:1], v[2:3]
	v_pk_add_f32 v[206:207], v[4:5], v[6:7]
	v_pk_add_f32 v[208:209], v[8:9], v[10:11]
	v_pk_add_f32 v[210:211], v[12:13], v[14:15]
	v_pk_add_f32 v[216:217], v[16:17], v[18:19]
	v_pk_add_f32 v[218:219], v[20:21], v[22:23]
	v_pk_add_f32 v[220:221], v[24:25], v[26:27]
	v_pk_add_f32 v[222:223], v[28:29], v[30:31]
	v_pk_add_f32 v[204:205], v[204:205], v[206:207]
	v_pk_add_f32 v[208:209], v[208:209], v[210:211]
	v_pk_add_f32 v[216:217], v[216:217], v[218:219]
	v_pk_add_f32 v[220:221], v[220:221], v[222:223]
	v_pk_add_f32 v[204:205], v[204:205], v[208:209]
	v_pk_add_f32 v[216:217], v[216:217], v[220:221]
	v_add_f32_e32 v204, v204, v205
	v_add_f32_e32 v216, v216, v217
	s_nop 1
	v_add_f32_dpp v204, v204, v204 row_ror:1 row_mask:0xf bank_mask:0xf bound_ctrl:1
	v_add_f32_dpp v216, v216, v216 row_ror:1 row_mask:0xf bank_mask:0xf bound_ctrl:1
	s_nop 0
	v_add_f32_dpp v204, v204, v204 row_ror:2 row_mask:0xf bank_mask:0xf bound_ctrl:1
	v_add_f32_dpp v216, v216, v216 row_ror:2 row_mask:0xf bank_mask:0xf bound_ctrl:1
	s_nop 0
	v_add_f32_dpp v204, v204, v204 row_ror:4 row_mask:0xf bank_mask:0xf bound_ctrl:1
	v_add_f32_dpp v216, v216, v216 row_ror:4 row_mask:0xf bank_mask:0xf bound_ctrl:1
	s_nop 0
	v_add_f32_dpp v204, v204, v204 row_ror:8 row_mask:0xf bank_mask:0xf bound_ctrl:1
	v_add_f32_dpp v216, v216, v216 row_ror:8 row_mask:0xf bank_mask:0xf bound_ctrl:1
	s_nop 0
	v_mov_b32_e32 v205, v204
	v_mov_b32_e32 v217, v216
	s_nop 1
	v_permlane16_swap_b32_e32 v204, v205
	v_permlane16_swap_b32_e32 v216, v217
	s_nop 0
	v_add_f32_e32 v204, v204, v205
	v_add_f32_e32 v216, v216, v217
	v_mov_b32_e32 v205, v204
	v_mov_b32_e32 v217, v216
	s_nop 1
	v_permlane32_swap_b32_e32 v204, v205
	v_permlane32_swap_b32_e32 v216, v217
	s_nop 0
	v_add_f32_e32 v204, v204, v205
	v_add_f32_e32 v216, v216, v217
	v_mul_f32_e32 v212, 0x3a800000, v204
	v_mul_f32_e32 v224, 0x3a800000, v216
	v_pk_add_f32 v[0:1], v[0:1], v[212:213] op_sel_hi:[1,0] neg_lo:[0,1] neg_hi:[0,1]
	v_pk_add_f32 v[2:3], v[2:3], v[212:213] op_sel_hi:[1,0] neg_lo:[0,1] neg_hi:[0,1]
	v_pk_add_f32 v[4:5], v[4:5], v[212:213] op_sel_hi:[1,0] neg_lo:[0,1] neg_hi:[0,1]
	v_pk_add_f32 v[6:7], v[6:7], v[212:213] op_sel_hi:[1,0] neg_lo:[0,1] neg_hi:[0,1]
	v_pk_add_f32 v[8:9], v[8:9], v[212:213] op_sel_hi:[1,0] neg_lo:[0,1] neg_hi:[0,1]
	v_pk_add_f32 v[10:11], v[10:11], v[212:213] op_sel_hi:[1,0] neg_lo:[0,1] neg_hi:[0,1]
	v_pk_add_f32 v[12:13], v[12:13], v[212:213] op_sel_hi:[1,0] neg_lo:[0,1] neg_hi:[0,1]
	v_pk_add_f32 v[14:15], v[14:15], v[212:213] op_sel_hi:[1,0] neg_lo:[0,1] neg_hi:[0,1]
	v_pk_add_f32 v[16:17], v[16:17], v[224:225] op_sel_hi:[1,0] neg_lo:[0,1] neg_hi:[0,1]
	v_pk_add_f32 v[18:19], v[18:19], v[224:225] op_sel_hi:[1,0] neg_lo:[0,1] neg_hi:[0,1]
	v_pk_add_f32 v[20:21], v[20:21], v[224:225] op_sel_hi:[1,0] neg_lo:[0,1] neg_hi:[0,1]
	v_pk_add_f32 v[22:23], v[22:23], v[224:225] op_sel_hi:[1,0] neg_lo:[0,1] neg_hi:[0,1]
	v_pk_add_f32 v[24:25], v[24:25], v[224:225] op_sel_hi:[1,0] neg_lo:[0,1] neg_hi:[0,1]
	v_pk_add_f32 v[26:27], v[26:27], v[224:225] op_sel_hi:[1,0] neg_lo:[0,1] neg_hi:[0,1]
	v_pk_add_f32 v[28:29], v[28:29], v[224:225] op_sel_hi:[1,0] neg_lo:[0,1] neg_hi:[0,1]
	v_pk_add_f32 v[30:31], v[30:31], v[224:225] op_sel_hi:[1,0] neg_lo:[0,1] neg_hi:[0,1]
	v_pk_mul_f32 v[204:205], v[0:1], v[0:1]
	v_pk_mul_f32 v[206:207], v[2:3], v[2:3]
	v_pk_mul_f32 v[216:217], v[16:17], v[16:17]
	v_pk_mul_f32 v[218:219], v[18:19], v[18:19]
	v_pk_fma_f32 v[204:205], v[4:5], v[4:5], v[204:205]
	v_pk_fma_f32 v[206:207], v[6:7], v[6:7], v[206:207]
	v_pk_fma_f32 v[216:217], v[20:21], v[20:21], v[216:217]
	v_pk_fma_f32 v[218:219], v[22:23], v[22:23], v[218:219]
	v_pk_fma_f32 v[204:205], v[8:9], v[8:9], v[204:205]
	v_pk_fma_f32 v[206:207], v[10:11], v[10:11], v[206:207]
	v_pk_fma_f32 v[216:217], v[24:25], v[24:25], v[216:217]
	v_pk_fma_f32 v[218:219], v[26:27], v[26:27], v[218:219]
	v_pk_fma_f32 v[204:205], v[12:13], v[12:13], v[204:205]
	v_pk_fma_f32 v[206:207], v[14:15], v[14:15], v[206:207]
	v_pk_fma_f32 v[216:217], v[28:29], v[28:29], v[216:217]
	v_pk_fma_f32 v[218:219], v[30:31], v[30:31], v[218:219]
	v_pk_add_f32 v[204:205], v[204:205], v[206:207]
	v_pk_add_f32 v[216:217], v[216:217], v[218:219]
	v_add_f32_e32 v204, v204, v205
	v_add_f32_e32 v216, v216, v217
	s_nop 1
	v_add_f32_dpp v204, v204, v204 row_ror:1 row_mask:0xf bank_mask:0xf bound_ctrl:1
	v_add_f32_dpp v216, v216, v216 row_ror:1 row_mask:0xf bank_mask:0xf bound_ctrl:1
	s_nop 0
	v_add_f32_dpp v204, v204, v204 row_ror:2 row_mask:0xf bank_mask:0xf bound_ctrl:1
	v_add_f32_dpp v216, v216, v216 row_ror:2 row_mask:0xf bank_mask:0xf bound_ctrl:1
	s_nop 0
	v_add_f32_dpp v204, v204, v204 row_ror:4 row_mask:0xf bank_mask:0xf bound_ctrl:1
	v_add_f32_dpp v216, v216, v216 row_ror:4 row_mask:0xf bank_mask:0xf bound_ctrl:1
	s_nop 0
	v_add_f32_dpp v204, v204, v204 row_ror:8 row_mask:0xf bank_mask:0xf bound_ctrl:1
	v_add_f32_dpp v216, v216, v216 row_ror:8 row_mask:0xf bank_mask:0xf bound_ctrl:1
	s_nop 0
	v_mov_b32_e32 v205, v204
	v_mov_b32_e32 v217, v216
	s_nop 1
	v_permlane16_swap_b32_e32 v204, v205
	v_permlane16_swap_b32_e32 v216, v217
	s_nop 0
	v_add_f32_e32 v204, v204, v205
	v_add_f32_e32 v216, v216, v217
	v_mov_b32_e32 v205, v204
	v_mov_b32_e32 v217, v216
	s_nop 1
	v_permlane32_swap_b32_e32 v204, v205
	v_permlane32_swap_b32_e32 v216, v217
	s_nop 0
	v_add_f32_e32 v204, v204, v205
	v_add_f32_e32 v216, v216, v217
	v_mov_b32_e32 v205, 0x3727c5ac
	v_fmac_f32_e32 v205, 0x3a800000, v204
	v_mov_b32_e32 v217, 0x3727c5ac
	v_fmac_f32_e32 v217, 0x3a800000, v216
	v_mul_f32_e32 v206, 0x4b800000, v205
	s_mov_b32 s4, 0x800000
	v_cmp_gt_f32_e32 vcc, s4, v205
	s_nop 1
	v_cndmask_b32_e32 v205, v205, v206, vcc
	v_rsq_f32_e32 v205, v205
	s_nop 0
	v_mul_f32_e32 v206, 0x45800000, v205
	v_cndmask_b32_e32 v214, v205, v206, vcc
	v_mul_f32_e32 v218, 0x4b800000, v217
	s_mov_b32 s4, 0x800000
	v_cmp_gt_f32_e32 vcc, s4, v217
	s_nop 1
	v_cndmask_b32_e32 v217, v217, v218, vcc
	v_rsq_f32_e32 v217, v217
	s_nop 0
	v_mul_f32_e32 v218, 0x45800000, v217
	v_cndmask_b32_e32 v226, v217, v218, vcc
	v_pk_mul_f32 v[0:1], v[0:1], v[214:215] op_sel_hi:[1,0]
	v_pk_mul_f32 v[2:3], v[2:3], v[214:215] op_sel_hi:[1,0]
	v_pk_mul_f32 v[4:5], v[4:5], v[214:215] op_sel_hi:[1,0]
	v_pk_mul_f32 v[6:7], v[6:7], v[214:215] op_sel_hi:[1,0]
	v_pk_mul_f32 v[8:9], v[8:9], v[214:215] op_sel_hi:[1,0]
	v_pk_mul_f32 v[10:11], v[10:11], v[214:215] op_sel_hi:[1,0]
	v_pk_mul_f32 v[12:13], v[12:13], v[214:215] op_sel_hi:[1,0]
	v_pk_mul_f32 v[14:15], v[14:15], v[214:215] op_sel_hi:[1,0]
	v_pk_mul_f32 v[16:17], v[16:17], v[226:227] op_sel_hi:[1,0]
	v_pk_mul_f32 v[18:19], v[18:19], v[226:227] op_sel_hi:[1,0]
	v_pk_mul_f32 v[20:21], v[20:21], v[226:227] op_sel_hi:[1,0]
	v_pk_mul_f32 v[22:23], v[22:23], v[226:227] op_sel_hi:[1,0]
	v_pk_mul_f32 v[24:25], v[24:25], v[226:227] op_sel_hi:[1,0]
	v_pk_mul_f32 v[26:27], v[26:27], v[226:227] op_sel_hi:[1,0]
	v_pk_mul_f32 v[28:29], v[28:29], v[226:227] op_sel_hi:[1,0]
	v_pk_mul_f32 v[30:31], v[30:31], v[226:227] op_sel_hi:[1,0]
	v_pk_fma_f32 v[0:1], v[136:137], v[0:1], v[152:153]
	v_pk_fma_f32 v[2:3], v[138:139], v[2:3], v[154:155]
	v_pk_fma_f32 v[4:5], v[140:141], v[4:5], v[156:157]
	v_pk_fma_f32 v[6:7], v[142:143], v[6:7], v[158:159]
	v_pk_fma_f32 v[8:9], v[144:145], v[8:9], v[160:161]
	v_pk_fma_f32 v[10:11], v[146:147], v[10:11], v[162:163]
	v_pk_fma_f32 v[12:13], v[148:149], v[12:13], v[164:165]
	v_pk_fma_f32 v[14:15], v[150:151], v[14:15], v[166:167]
	v_pk_fma_f32 v[16:17], v[136:137], v[16:17], v[152:153]
	v_pk_fma_f32 v[18:19], v[138:139], v[18:19], v[154:155]
	v_pk_fma_f32 v[20:21], v[140:141], v[20:21], v[156:157]
	v_pk_fma_f32 v[22:23], v[142:143], v[22:23], v[158:159]
	v_pk_fma_f32 v[24:25], v[144:145], v[24:25], v[160:161]
	v_pk_fma_f32 v[26:27], v[146:147], v[26:27], v[162:163]
	v_pk_fma_f32 v[28:29], v[148:149], v[28:29], v[164:165]
	v_pk_fma_f32 v[30:31], v[150:151], v[30:31], v[166:167]
	v_mov_b32_e32 v228, v212
	v_mov_b32_e32 v229, v214
	v_mov_b32_e32 v168, v224
	v_mov_b32_e32 v169, v226
	v_add_f32_e32 v80, 1.0, v80
	v_add_f32_e32 v81, 1.0, v81
	v_add_f32_e32 v82, 1.0, v82
	v_add_f32_e32 v83, 1.0, v83
	v_add_f32_e32 v84, 1.0, v84
	v_add_f32_e32 v85, 1.0, v85
	v_add_f32_e32 v86, 1.0, v86
	v_add_f32_e32 v87, 1.0, v87
	v_add_f32_e32 v88, 1.0, v88
	v_add_f32_e32 v89, 1.0, v89
	v_add_f32_e32 v90, 1.0, v90
	v_add_f32_e32 v91, 1.0, v91
	v_add_f32_e32 v92, 1.0, v92
	v_add_f32_e32 v93, 1.0, v93
	v_add_f32_e32 v94, 1.0, v94
	v_add_f32_e32 v95, 1.0, v95
	v_pk_fma_f32 v[204:205], v[80:81], v[0:1], v[64:65]
	v_pk_fma_f32 v[206:207], v[82:83], v[2:3], v[66:67]
	v_pk_fma_f32 v[208:209], v[84:85], v[4:5], v[68:69]
	v_pk_fma_f32 v[210:211], v[86:87], v[6:7], v[70:71]
	v_pk_fma_f32 v[212:213], v[88:89], v[8:9], v[72:73]
	v_pk_fma_f32 v[214:215], v[90:91], v[10:11], v[74:75]
	v_pk_fma_f32 v[216:217], v[92:93], v[12:13], v[76:77]
	v_pk_fma_f32 v[218:219], v[94:95], v[14:15], v[78:79]
	v_cvt_pk_bf16_f32 v220, v204, v205
	v_cvt_pk_bf16_f32 v221, v206, v207
	v_cvt_pk_bf16_f32 v222, v208, v209
	v_cvt_pk_bf16_f32 v223, v210, v211
	v_cvt_pk_bf16_f32 v224, v212, v213
	v_cvt_pk_bf16_f32 v225, v214, v215
	v_cvt_pk_bf16_f32 v226, v216, v217
	v_cvt_pk_bf16_f32 v227, v218, v219
	s_mul_i32 s4, s6, 0x880
	s_add_u32 s4, s4, 0xe166000
	s_add_u32 s4, s4, s8
	s_addc_u32 s5, s9, 0
	global_store_dwordx2 v233, v[220:221], s[4:5]
	global_store_dwordx2 v233, v[222:223], s[4:5] offset:512
	global_store_dwordx2 v233, v[224:225], s[4:5] offset:1024
	global_store_dwordx2 v233, v[226:227], s[4:5] offset:1536
	s_mov_b64 s[12:13], exec
	s_mov_b64 exec, 1
	global_store_dwordx2 v129, v[228:229], s[4:5] offset:2048
	s_mov_b64 exec, s[12:13]
	v_pk_fma_f32 v[204:205], v[80:81], v[16:17], v[64:65]
	v_pk_fma_f32 v[206:207], v[82:83], v[18:19], v[66:67]
	v_pk_fma_f32 v[208:209], v[84:85], v[20:21], v[68:69]
	v_pk_fma_f32 v[210:211], v[86:87], v[22:23], v[70:71]
	v_pk_fma_f32 v[212:213], v[88:89], v[24:25], v[72:73]
	v_pk_fma_f32 v[214:215], v[90:91], v[26:27], v[74:75]
	v_pk_fma_f32 v[216:217], v[92:93], v[28:29], v[76:77]
	v_pk_fma_f32 v[218:219], v[94:95], v[30:31], v[78:79]
	v_cvt_pk_bf16_f32 v220, v204, v205
	v_cvt_pk_bf16_f32 v221, v206, v207
	v_cvt_pk_bf16_f32 v222, v208, v209
	v_cvt_pk_bf16_f32 v223, v210, v211
	v_cvt_pk_bf16_f32 v224, v212, v213
	v_cvt_pk_bf16_f32 v225, v214, v215
	v_cvt_pk_bf16_f32 v226, v216, v217
	v_cvt_pk_bf16_f32 v227, v218, v219
	s_mul_i32 s4, s6, 0x880
	s_add_u32 s4, s4, 0xe5a6000
	s_add_u32 s4, s4, s8
	s_addc_u32 s5, s9, 0
	global_store_dwordx2 v233, v[220:221], s[4:5]
	global_store_dwordx2 v233, v[222:223], s[4:5] offset:512
	global_store_dwordx2 v233, v[224:225], s[4:5] offset:1024
	global_store_dwordx2 v233, v[226:227], s[4:5] offset:1536
	s_mov_b64 s[12:13], exec
	s_mov_b64 exec, 1
	global_store_dwordx2 v129, v[168:169], s[4:5] offset:2048
	s_mov_b64 exec, s[12:13]
	s_lshl_b32 s4, s6, 12
	s_add_u32 s4, s4, 0xd166000
	s_add_u32 s4, s4, s8
	s_addc_u32 s5, s9, 0
	global_load_dwordx4 v[0:3], v232, s[4:5]
	global_load_dwordx4 v[4:7], v232, s[4:5] offset:1024
	global_load_dwordx4 v[8:11], v232, s[4:5] offset:2048
	global_load_dwordx4 v[12:15], v232, s[4:5] offset:3072
	s_lshl_b32 s4, s6, 12
	s_add_u32 s4, s4, 0xd966000
	s_add_u32 s4, s4, s8
	s_addc_u32 s5, s9, 0
	global_load_dwordx4 v[16:19], v232, s[4:5]
	global_load_dwordx4 v[20:23], v232, s[4:5] offset:1024
	global_load_dwordx4 v[24:27], v232, s[4:5] offset:2048
	global_load_dwordx4 v[28:31], v232, s[4:5] offset:3072
	s_add_u32 s4, s10, 0x12000
	s_addc_u32 s5, s11, 0
	global_load_dwordx4 v[64:67], v232, s[4:5]
	global_load_dwordx4 v[68:71], v232, s[4:5] offset:1024
	global_load_dwordx4 v[72:75], v232, s[4:5] offset:2048
	global_load_dwordx4 v[76:79], v232, s[4:5] offset:3072
	s_add_u32 s4, s4, 0x1000
	s_addc_u32 s5, s5, 0
	global_load_dwordx4 v[80:83], v232, s[4:5]
	global_load_dwordx4 v[84:87], v232, s[4:5] offset:1024
	global_load_dwordx4 v[88:91], v232, s[4:5] offset:2048
	global_load_dwordx4 v[92:95], v232, s[4:5] offset:3072
	s_waitcnt vmcnt(26)
	v_pk_add_f32 v[204:205], v[32:33], v[34:35]
	v_pk_add_f32 v[206:207], v[36:37], v[38:39]
	v_pk_add_f32 v[208:209], v[40:41], v[42:43]
	v_pk_add_f32 v[210:211], v[44:45], v[46:47]
	v_pk_add_f32 v[216:217], v[48:49], v[50:51]
	v_pk_add_f32 v[218:219], v[52:53], v[54:55]
	v_pk_add_f32 v[220:221], v[56:57], v[58:59]
	v_pk_add_f32 v[222:223], v[60:61], v[62:63]
	v_pk_add_f32 v[204:205], v[204:205], v[206:207]
	v_pk_add_f32 v[208:209], v[208:209], v[210:211]
	v_pk_add_f32 v[216:217], v[216:217], v[218:219]
	v_pk_add_f32 v[220:221], v[220:221], v[222:223]
	v_pk_add_f32 v[204:205], v[204:205], v[208:209]
	v_pk_add_f32 v[216:217], v[216:217], v[220:221]
	v_add_f32_e32 v204, v204, v205
	v_add_f32_e32 v216, v216, v217
	s_nop 1
	v_add_f32_dpp v204, v204, v204 row_ror:1 row_mask:0xf bank_mask:0xf bound_ctrl:1
	v_add_f32_dpp v216, v216, v216 row_ror:1 row_mask:0xf bank_mask:0xf bound_ctrl:1
	s_nop 0
	v_add_f32_dpp v204, v204, v204 row_ror:2 row_mask:0xf bank_mask:0xf bound_ctrl:1
	v_add_f32_dpp v216, v216, v216 row_ror:2 row_mask:0xf bank_mask:0xf bound_ctrl:1
	s_nop 0
	v_add_f32_dpp v204, v204, v204 row_ror:4 row_mask:0xf bank_mask:0xf bound_ctrl:1
	v_add_f32_dpp v216, v216, v216 row_ror:4 row_mask:0xf bank_mask:0xf bound_ctrl:1
	s_nop 0
	v_add_f32_dpp v204, v204, v204 row_ror:8 row_mask:0xf bank_mask:0xf bound_ctrl:1
	v_add_f32_dpp v216, v216, v216 row_ror:8 row_mask:0xf bank_mask:0xf bound_ctrl:1
	s_nop 0
	v_mov_b32_e32 v205, v204
	v_mov_b32_e32 v217, v216
	s_nop 1
	v_permlane16_swap_b32_e32 v204, v205
	v_permlane16_swap_b32_e32 v216, v217
	s_nop 0
	v_add_f32_e32 v204, v204, v205
	v_add_f32_e32 v216, v216, v217
	v_mov_b32_e32 v205, v204
	v_mov_b32_e32 v217, v216
	s_nop 1
	v_permlane32_swap_b32_e32 v204, v205
	v_permlane32_swap_b32_e32 v216, v217
	s_nop 0
	v_add_f32_e32 v204, v204, v205
	v_add_f32_e32 v216, v216, v217
	v_mul_f32_e32 v212, 0x3a800000, v204
	v_mul_f32_e32 v224, 0x3a800000, v216
	v_pk_add_f32 v[32:33], v[32:33], v[212:213] op_sel_hi:[1,0] neg_lo:[0,1] neg_hi:[0,1]
	v_pk_add_f32 v[34:35], v[34:35], v[212:213] op_sel_hi:[1,0] neg_lo:[0,1] neg_hi:[0,1]
	v_pk_add_f32 v[36:37], v[36:37], v[212:213] op_sel_hi:[1,0] neg_lo:[0,1] neg_hi:[0,1]
	v_pk_add_f32 v[38:39], v[38:39], v[212:213] op_sel_hi:[1,0] neg_lo:[0,1] neg_hi:[0,1]
	v_pk_add_f32 v[40:41], v[40:41], v[212:213] op_sel_hi:[1,0] neg_lo:[0,1] neg_hi:[0,1]
	v_pk_add_f32 v[42:43], v[42:43], v[212:213] op_sel_hi:[1,0] neg_lo:[0,1] neg_hi:[0,1]
	v_pk_add_f32 v[44:45], v[44:45], v[212:213] op_sel_hi:[1,0] neg_lo:[0,1] neg_hi:[0,1]
	v_pk_add_f32 v[46:47], v[46:47], v[212:213] op_sel_hi:[1,0] neg_lo:[0,1] neg_hi:[0,1]
	v_pk_add_f32 v[48:49], v[48:49], v[224:225] op_sel_hi:[1,0] neg_lo:[0,1] neg_hi:[0,1]
	v_pk_add_f32 v[50:51], v[50:51], v[224:225] op_sel_hi:[1,0] neg_lo:[0,1] neg_hi:[0,1]
	v_pk_add_f32 v[52:53], v[52:53], v[224:225] op_sel_hi:[1,0] neg_lo:[0,1] neg_hi:[0,1]
	v_pk_add_f32 v[54:55], v[54:55], v[224:225] op_sel_hi:[1,0] neg_lo:[0,1] neg_hi:[0,1]
	v_pk_add_f32 v[56:57], v[56:57], v[224:225] op_sel_hi:[1,0] neg_lo:[0,1] neg_hi:[0,1]
	v_pk_add_f32 v[58:59], v[58:59], v[224:225] op_sel_hi:[1,0] neg_lo:[0,1] neg_hi:[0,1]
	v_pk_add_f32 v[60:61], v[60:61], v[224:225] op_sel_hi:[1,0] neg_lo:[0,1] neg_hi:[0,1]
	v_pk_add_f32 v[62:63], v[62:63], v[224:225] op_sel_hi:[1,0] neg_lo:[0,1] neg_hi:[0,1]
	v_pk_mul_f32 v[204:205], v[32:33], v[32:33]
	v_pk_mul_f32 v[206:207], v[34:35], v[34:35]
	v_pk_mul_f32 v[216:217], v[48:49], v[48:49]
	v_pk_mul_f32 v[218:219], v[50:51], v[50:51]
	v_pk_fma_f32 v[204:205], v[36:37], v[36:37], v[204:205]
	v_pk_fma_f32 v[206:207], v[38:39], v[38:39], v[206:207]
	v_pk_fma_f32 v[216:217], v[52:53], v[52:53], v[216:217]
	v_pk_fma_f32 v[218:219], v[54:55], v[54:55], v[218:219]
	v_pk_fma_f32 v[204:205], v[40:41], v[40:41], v[204:205]
	v_pk_fma_f32 v[206:207], v[42:43], v[42:43], v[206:207]
	v_pk_fma_f32 v[216:217], v[56:57], v[56:57], v[216:217]
	v_pk_fma_f32 v[218:219], v[58:59], v[58:59], v[218:219]
	v_pk_fma_f32 v[204:205], v[44:45], v[44:45], v[204:205]
	v_pk_fma_f32 v[206:207], v[46:47], v[46:47], v[206:207]
	v_pk_fma_f32 v[216:217], v[60:61], v[60:61], v[216:217]
	v_pk_fma_f32 v[218:219], v[62:63], v[62:63], v[218:219]
	v_pk_add_f32 v[204:205], v[204:205], v[206:207]
	v_pk_add_f32 v[216:217], v[216:217], v[218:219]
	v_add_f32_e32 v204, v204, v205
	v_add_f32_e32 v216, v216, v217
	s_nop 1
	v_add_f32_dpp v204, v204, v204 row_ror:1 row_mask:0xf bank_mask:0xf bound_ctrl:1
	v_add_f32_dpp v216, v216, v216 row_ror:1 row_mask:0xf bank_mask:0xf bound_ctrl:1
	s_nop 0
	v_add_f32_dpp v204, v204, v204 row_ror:2 row_mask:0xf bank_mask:0xf bound_ctrl:1
	v_add_f32_dpp v216, v216, v216 row_ror:2 row_mask:0xf bank_mask:0xf bound_ctrl:1
	s_nop 0
	v_add_f32_dpp v204, v204, v204 row_ror:4 row_mask:0xf bank_mask:0xf bound_ctrl:1
	v_add_f32_dpp v216, v216, v216 row_ror:4 row_mask:0xf bank_mask:0xf bound_ctrl:1
	s_nop 0
	v_add_f32_dpp v204, v204, v204 row_ror:8 row_mask:0xf bank_mask:0xf bound_ctrl:1
	v_add_f32_dpp v216, v216, v216 row_ror:8 row_mask:0xf bank_mask:0xf bound_ctrl:1
	s_nop 0
	v_mov_b32_e32 v205, v204
	v_mov_b32_e32 v217, v216
	s_nop 1
	v_permlane16_swap_b32_e32 v204, v205
	v_permlane16_swap_b32_e32 v216, v217
	s_nop 0
	v_add_f32_e32 v204, v204, v205
	v_add_f32_e32 v216, v216, v217
	v_mov_b32_e32 v205, v204
	v_mov_b32_e32 v217, v216
	s_nop 1
	v_permlane32_swap_b32_e32 v204, v205
	v_permlane32_swap_b32_e32 v216, v217
	s_nop 0
	v_add_f32_e32 v204, v204, v205
	v_add_f32_e32 v216, v216, v217
	v_mov_b32_e32 v205, 0x3727c5ac
	v_fmac_f32_e32 v205, 0x3a800000, v204
	v_mov_b32_e32 v217, 0x3727c5ac
	v_fmac_f32_e32 v217, 0x3a800000, v216
	v_mul_f32_e32 v206, 0x4b800000, v205
	s_mov_b32 s4, 0x800000
	v_cmp_gt_f32_e32 vcc, s4, v205
	s_nop 1
	v_cndmask_b32_e32 v205, v205, v206, vcc
	v_rsq_f32_e32 v205, v205
	s_nop 0
	v_mul_f32_e32 v206, 0x45800000, v205
	v_cndmask_b32_e32 v214, v205, v206, vcc
	v_mul_f32_e32 v218, 0x4b800000, v217
	s_mov_b32 s4, 0x800000
	v_cmp_gt_f32_e32 vcc, s4, v217
	s_nop 1
	v_cndmask_b32_e32 v217, v217, v218, vcc
	v_rsq_f32_e32 v217, v217
	s_nop 0
	v_mul_f32_e32 v218, 0x45800000, v217
	v_cndmask_b32_e32 v226, v217, v218, vcc
	v_pk_mul_f32 v[32:33], v[32:33], v[214:215] op_sel_hi:[1,0]
	v_pk_mul_f32 v[34:35], v[34:35], v[214:215] op_sel_hi:[1,0]
	v_pk_mul_f32 v[36:37], v[36:37], v[214:215] op_sel_hi:[1,0]
	v_pk_mul_f32 v[38:39], v[38:39], v[214:215] op_sel_hi:[1,0]
	v_pk_mul_f32 v[40:41], v[40:41], v[214:215] op_sel_hi:[1,0]
	v_pk_mul_f32 v[42:43], v[42:43], v[214:215] op_sel_hi:[1,0]
	v_pk_mul_f32 v[44:45], v[44:45], v[214:215] op_sel_hi:[1,0]
	v_pk_mul_f32 v[46:47], v[46:47], v[214:215] op_sel_hi:[1,0]
	v_pk_mul_f32 v[48:49], v[48:49], v[226:227] op_sel_hi:[1,0]
	v_pk_mul_f32 v[50:51], v[50:51], v[226:227] op_sel_hi:[1,0]
	v_pk_mul_f32 v[52:53], v[52:53], v[226:227] op_sel_hi:[1,0]
	v_pk_mul_f32 v[54:55], v[54:55], v[226:227] op_sel_hi:[1,0]
	v_pk_mul_f32 v[56:57], v[56:57], v[226:227] op_sel_hi:[1,0]
	v_pk_mul_f32 v[58:59], v[58:59], v[226:227] op_sel_hi:[1,0]
	v_pk_mul_f32 v[60:61], v[60:61], v[226:227] op_sel_hi:[1,0]
	v_pk_mul_f32 v[62:63], v[62:63], v[226:227] op_sel_hi:[1,0]
	v_pk_fma_f32 v[32:33], v[136:137], v[32:33], v[152:153]
	v_pk_fma_f32 v[34:35], v[138:139], v[34:35], v[154:155]
	v_pk_fma_f32 v[36:37], v[140:141], v[36:37], v[156:157]
	v_pk_fma_f32 v[38:39], v[142:143], v[38:39], v[158:159]
	v_pk_fma_f32 v[40:41], v[144:145], v[40:41], v[160:161]
	v_pk_fma_f32 v[42:43], v[146:147], v[42:43], v[162:163]
	v_pk_fma_f32 v[44:45], v[148:149], v[44:45], v[164:165]
	v_pk_fma_f32 v[46:47], v[150:151], v[46:47], v[166:167]
	v_pk_fma_f32 v[48:49], v[136:137], v[48:49], v[152:153]
	v_pk_fma_f32 v[50:51], v[138:139], v[50:51], v[154:155]
	v_pk_fma_f32 v[52:53], v[140:141], v[52:53], v[156:157]
	v_pk_fma_f32 v[54:55], v[142:143], v[54:55], v[158:159]
	v_pk_fma_f32 v[56:57], v[144:145], v[56:57], v[160:161]
	v_pk_fma_f32 v[58:59], v[146:147], v[58:59], v[162:163]
	v_pk_fma_f32 v[60:61], v[148:149], v[60:61], v[164:165]
	v_pk_fma_f32 v[62:63], v[150:151], v[62:63], v[166:167]
	v_mov_b32_e32 v228, v212
	v_mov_b32_e32 v229, v214
	v_mov_b32_e32 v168, v224
	v_mov_b32_e32 v169, v226
	v_add_f32_e32 v112, 1.0, v112
	v_add_f32_e32 v113, 1.0, v113
	v_add_f32_e32 v114, 1.0, v114
	v_add_f32_e32 v115, 1.0, v115
	v_add_f32_e32 v116, 1.0, v116
	v_add_f32_e32 v117, 1.0, v117
	v_add_f32_e32 v118, 1.0, v118
	v_add_f32_e32 v119, 1.0, v119
	v_add_f32_e32 v120, 1.0, v120
	v_add_f32_e32 v121, 1.0, v121
	v_add_f32_e32 v122, 1.0, v122
	v_add_f32_e32 v123, 1.0, v123
	v_add_f32_e32 v124, 1.0, v124
	v_add_f32_e32 v125, 1.0, v125
	v_add_f32_e32 v126, 1.0, v126
	v_add_f32_e32 v127, 1.0, v127
	v_pk_fma_f32 v[204:205], v[112:113], v[32:33], v[96:97]
	v_pk_fma_f32 v[206:207], v[114:115], v[34:35], v[98:99]
	v_pk_fma_f32 v[208:209], v[116:117], v[36:37], v[100:101]
	v_pk_fma_f32 v[210:211], v[118:119], v[38:39], v[102:103]
	v_pk_fma_f32 v[212:213], v[120:121], v[40:41], v[104:105]
	v_pk_fma_f32 v[214:215], v[122:123], v[42:43], v[106:107]
	v_pk_fma_f32 v[216:217], v[124:125], v[44:45], v[108:109]
	v_pk_fma_f32 v[218:219], v[126:127], v[46:47], v[110:111]
	v_cvt_pk_bf16_f32 v220, v204, v205
	v_cvt_pk_bf16_f32 v221, v206, v207
	v_cvt_pk_bf16_f32 v222, v208, v209
	v_cvt_pk_bf16_f32 v223, v210, v211
	v_cvt_pk_bf16_f32 v224, v212, v213
	v_cvt_pk_bf16_f32 v225, v214, v215
	v_cvt_pk_bf16_f32 v226, v216, v217
	v_cvt_pk_bf16_f32 v227, v218, v219
	s_mul_i32 s4, s6, 0x880
	s_add_u32 s4, s4, 0xe9e6000
	s_add_u32 s4, s4, s8
	s_addc_u32 s5, s9, 0
	global_store_dwordx2 v233, v[220:221], s[4:5]
	global_store_dwordx2 v233, v[222:223], s[4:5] offset:512
	global_store_dwordx2 v233, v[224:225], s[4:5] offset:1024
	global_store_dwordx2 v233, v[226:227], s[4:5] offset:1536
	s_mov_b64 s[12:13], exec
	s_mov_b64 exec, 1
	global_store_dwordx2 v129, v[228:229], s[4:5] offset:2048
	s_mov_b64 exec, s[12:13]
	v_pk_fma_f32 v[204:205], v[112:113], v[48:49], v[96:97]
	v_pk_fma_f32 v[206:207], v[114:115], v[50:51], v[98:99]
	v_pk_fma_f32 v[208:209], v[116:117], v[52:53], v[100:101]
	v_pk_fma_f32 v[210:211], v[118:119], v[54:55], v[102:103]
	v_pk_fma_f32 v[212:213], v[120:121], v[56:57], v[104:105]
	v_pk_fma_f32 v[214:215], v[122:123], v[58:59], v[106:107]
	v_pk_fma_f32 v[216:217], v[124:125], v[60:61], v[108:109]
	v_pk_fma_f32 v[218:219], v[126:127], v[62:63], v[110:111]
	v_cvt_pk_bf16_f32 v220, v204, v205
	v_cvt_pk_bf16_f32 v221, v206, v207
	v_cvt_pk_bf16_f32 v222, v208, v209
	v_cvt_pk_bf16_f32 v223, v210, v211
	v_cvt_pk_bf16_f32 v224, v212, v213
	v_cvt_pk_bf16_f32 v225, v214, v215
	v_cvt_pk_bf16_f32 v226, v216, v217
	v_cvt_pk_bf16_f32 v227, v218, v219
	s_mul_i32 s4, s6, 0x880
	s_add_u32 s4, s4, 0xee26000
	s_add_u32 s4, s4, s8
	s_addc_u32 s5, s9, 0
	global_store_dwordx2 v233, v[220:221], s[4:5]
	global_store_dwordx2 v233, v[222:223], s[4:5] offset:512
	global_store_dwordx2 v233, v[224:225], s[4:5] offset:1024
	global_store_dwordx2 v233, v[226:227], s[4:5] offset:1536
	s_mov_b64 s[12:13], exec
	s_mov_b64 exec, 1
	global_store_dwordx2 v129, v[168:169], s[4:5] offset:2048
	s_mov_b64 exec, s[12:13]
	s_waitcnt vmcnt(10)
	v_pk_add_f32 v[204:205], v[0:1], v[2:3]
	v_pk_add_f32 v[206:207], v[4:5], v[6:7]
	v_pk_add_f32 v[208:209], v[8:9], v[10:11]
	v_pk_add_f32 v[210:211], v[12:13], v[14:15]
	v_pk_add_f32 v[216:217], v[16:17], v[18:19]
	v_pk_add_f32 v[218:219], v[20:21], v[22:23]
	v_pk_add_f32 v[220:221], v[24:25], v[26:27]
	v_pk_add_f32 v[222:223], v[28:29], v[30:31]
	v_pk_add_f32 v[204:205], v[204:205], v[206:207]
	v_pk_add_f32 v[208:209], v[208:209], v[210:211]
	v_pk_add_f32 v[216:217], v[216:217], v[218:219]
	v_pk_add_f32 v[220:221], v[220:221], v[222:223]
	v_pk_add_f32 v[204:205], v[204:205], v[208:209]
	v_pk_add_f32 v[216:217], v[216:217], v[220:221]
	v_add_f32_e32 v204, v204, v205
	v_add_f32_e32 v216, v216, v217
	s_nop 1
	v_add_f32_dpp v204, v204, v204 row_ror:1 row_mask:0xf bank_mask:0xf bound_ctrl:1
	v_add_f32_dpp v216, v216, v216 row_ror:1 row_mask:0xf bank_mask:0xf bound_ctrl:1
	s_nop 0
	v_add_f32_dpp v204, v204, v204 row_ror:2 row_mask:0xf bank_mask:0xf bound_ctrl:1
	v_add_f32_dpp v216, v216, v216 row_ror:2 row_mask:0xf bank_mask:0xf bound_ctrl:1
	s_nop 0
	v_add_f32_dpp v204, v204, v204 row_ror:4 row_mask:0xf bank_mask:0xf bound_ctrl:1
	v_add_f32_dpp v216, v216, v216 row_ror:4 row_mask:0xf bank_mask:0xf bound_ctrl:1
	s_nop 0
	v_add_f32_dpp v204, v204, v204 row_ror:8 row_mask:0xf bank_mask:0xf bound_ctrl:1
	v_add_f32_dpp v216, v216, v216 row_ror:8 row_mask:0xf bank_mask:0xf bound_ctrl:1
	s_nop 0
	v_mov_b32_e32 v205, v204
	v_mov_b32_e32 v217, v216
	s_nop 1
	v_permlane16_swap_b32_e32 v204, v205
	v_permlane16_swap_b32_e32 v216, v217
	s_nop 0
	v_add_f32_e32 v204, v204, v205
	v_add_f32_e32 v216, v216, v217
	v_mov_b32_e32 v205, v204
	v_mov_b32_e32 v217, v216
	s_nop 1
	v_permlane32_swap_b32_e32 v204, v205
	v_permlane32_swap_b32_e32 v216, v217
	s_nop 0
	v_add_f32_e32 v204, v204, v205
	v_add_f32_e32 v216, v216, v217
	v_mul_f32_e32 v212, 0x3a800000, v204
	v_mul_f32_e32 v224, 0x3a800000, v216
	v_pk_add_f32 v[0:1], v[0:1], v[212:213] op_sel_hi:[1,0] neg_lo:[0,1] neg_hi:[0,1]
	v_pk_add_f32 v[2:3], v[2:3], v[212:213] op_sel_hi:[1,0] neg_lo:[0,1] neg_hi:[0,1]
	v_pk_add_f32 v[4:5], v[4:5], v[212:213] op_sel_hi:[1,0] neg_lo:[0,1] neg_hi:[0,1]
	v_pk_add_f32 v[6:7], v[6:7], v[212:213] op_sel_hi:[1,0] neg_lo:[0,1] neg_hi:[0,1]
	v_pk_add_f32 v[8:9], v[8:9], v[212:213] op_sel_hi:[1,0] neg_lo:[0,1] neg_hi:[0,1]
	v_pk_add_f32 v[10:11], v[10:11], v[212:213] op_sel_hi:[1,0] neg_lo:[0,1] neg_hi:[0,1]
	v_pk_add_f32 v[12:13], v[12:13], v[212:213] op_sel_hi:[1,0] neg_lo:[0,1] neg_hi:[0,1]
	v_pk_add_f32 v[14:15], v[14:15], v[212:213] op_sel_hi:[1,0] neg_lo:[0,1] neg_hi:[0,1]
	v_pk_add_f32 v[16:17], v[16:17], v[224:225] op_sel_hi:[1,0] neg_lo:[0,1] neg_hi:[0,1]
	v_pk_add_f32 v[18:19], v[18:19], v[224:225] op_sel_hi:[1,0] neg_lo:[0,1] neg_hi:[0,1]
	v_pk_add_f32 v[20:21], v[20:21], v[224:225] op_sel_hi:[1,0] neg_lo:[0,1] neg_hi:[0,1]
	v_pk_add_f32 v[22:23], v[22:23], v[224:225] op_sel_hi:[1,0] neg_lo:[0,1] neg_hi:[0,1]
	v_pk_add_f32 v[24:25], v[24:25], v[224:225] op_sel_hi:[1,0] neg_lo:[0,1] neg_hi:[0,1]
	v_pk_add_f32 v[26:27], v[26:27], v[224:225] op_sel_hi:[1,0] neg_lo:[0,1] neg_hi:[0,1]
	v_pk_add_f32 v[28:29], v[28:29], v[224:225] op_sel_hi:[1,0] neg_lo:[0,1] neg_hi:[0,1]
	v_pk_add_f32 v[30:31], v[30:31], v[224:225] op_sel_hi:[1,0] neg_lo:[0,1] neg_hi:[0,1]
	v_pk_mul_f32 v[204:205], v[0:1], v[0:1]
	v_pk_mul_f32 v[206:207], v[2:3], v[2:3]
	v_pk_mul_f32 v[216:217], v[16:17], v[16:17]
	v_pk_mul_f32 v[218:219], v[18:19], v[18:19]
	v_pk_fma_f32 v[204:205], v[4:5], v[4:5], v[204:205]
	v_pk_fma_f32 v[206:207], v[6:7], v[6:7], v[206:207]
	v_pk_fma_f32 v[216:217], v[20:21], v[20:21], v[216:217]
	v_pk_fma_f32 v[218:219], v[22:23], v[22:23], v[218:219]
	v_pk_fma_f32 v[204:205], v[8:9], v[8:9], v[204:205]
	v_pk_fma_f32 v[206:207], v[10:11], v[10:11], v[206:207]
	v_pk_fma_f32 v[216:217], v[24:25], v[24:25], v[216:217]
	v_pk_fma_f32 v[218:219], v[26:27], v[26:27], v[218:219]
	v_pk_fma_f32 v[204:205], v[12:13], v[12:13], v[204:205]
	v_pk_fma_f32 v[206:207], v[14:15], v[14:15], v[206:207]
	v_pk_fma_f32 v[216:217], v[28:29], v[28:29], v[216:217]
	v_pk_fma_f32 v[218:219], v[30:31], v[30:31], v[218:219]
	v_pk_add_f32 v[204:205], v[204:205], v[206:207]
	v_pk_add_f32 v[216:217], v[216:217], v[218:219]
	v_add_f32_e32 v204, v204, v205
	v_add_f32_e32 v216, v216, v217
	s_nop 1
	v_add_f32_dpp v204, v204, v204 row_ror:1 row_mask:0xf bank_mask:0xf bound_ctrl:1
	v_add_f32_dpp v216, v216, v216 row_ror:1 row_mask:0xf bank_mask:0xf bound_ctrl:1
	s_nop 0
	v_add_f32_dpp v204, v204, v204 row_ror:2 row_mask:0xf bank_mask:0xf bound_ctrl:1
	v_add_f32_dpp v216, v216, v216 row_ror:2 row_mask:0xf bank_mask:0xf bound_ctrl:1
	s_nop 0
	v_add_f32_dpp v204, v204, v204 row_ror:4 row_mask:0xf bank_mask:0xf bound_ctrl:1
	v_add_f32_dpp v216, v216, v216 row_ror:4 row_mask:0xf bank_mask:0xf bound_ctrl:1
	s_nop 0
	v_add_f32_dpp v204, v204, v204 row_ror:8 row_mask:0xf bank_mask:0xf bound_ctrl:1
	v_add_f32_dpp v216, v216, v216 row_ror:8 row_mask:0xf bank_mask:0xf bound_ctrl:1
	s_nop 0
	v_mov_b32_e32 v205, v204
	v_mov_b32_e32 v217, v216
	s_nop 1
	v_permlane16_swap_b32_e32 v204, v205
	v_permlane16_swap_b32_e32 v216, v217
	s_nop 0
	v_add_f32_e32 v204, v204, v205
	v_add_f32_e32 v216, v216, v217
	v_mov_b32_e32 v205, v204
	v_mov_b32_e32 v217, v216
	s_nop 1
	v_permlane32_swap_b32_e32 v204, v205
	v_permlane32_swap_b32_e32 v216, v217
	s_nop 0
	v_add_f32_e32 v204, v204, v205
	v_add_f32_e32 v216, v216, v217
	v_mov_b32_e32 v205, 0x3727c5ac
	v_fmac_f32_e32 v205, 0x3a800000, v204
	v_mov_b32_e32 v217, 0x3727c5ac
	v_fmac_f32_e32 v217, 0x3a800000, v216
	v_mul_f32_e32 v206, 0x4b800000, v205
	s_mov_b32 s4, 0x800000
	v_cmp_gt_f32_e32 vcc, s4, v205
	s_nop 1
	v_cndmask_b32_e32 v205, v205, v206, vcc
	v_rsq_f32_e32 v205, v205
	s_nop 0
	v_mul_f32_e32 v206, 0x45800000, v205
	v_cndmask_b32_e32 v214, v205, v206, vcc
	v_mul_f32_e32 v218, 0x4b800000, v217
	s_mov_b32 s4, 0x800000
	v_cmp_gt_f32_e32 vcc, s4, v217
	s_nop 1
	v_cndmask_b32_e32 v217, v217, v218, vcc
	v_rsq_f32_e32 v217, v217
	s_nop 0
	v_mul_f32_e32 v218, 0x45800000, v217
	v_cndmask_b32_e32 v226, v217, v218, vcc
	v_pk_mul_f32 v[0:1], v[0:1], v[214:215] op_sel_hi:[1,0]
	v_pk_mul_f32 v[2:3], v[2:3], v[214:215] op_sel_hi:[1,0]
	v_pk_mul_f32 v[4:5], v[4:5], v[214:215] op_sel_hi:[1,0]
	v_pk_mul_f32 v[6:7], v[6:7], v[214:215] op_sel_hi:[1,0]
	v_pk_mul_f32 v[8:9], v[8:9], v[214:215] op_sel_hi:[1,0]
	v_pk_mul_f32 v[10:11], v[10:11], v[214:215] op_sel_hi:[1,0]
	v_pk_mul_f32 v[12:13], v[12:13], v[214:215] op_sel_hi:[1,0]
	v_pk_mul_f32 v[14:15], v[14:15], v[214:215] op_sel_hi:[1,0]
	v_pk_mul_f32 v[16:17], v[16:17], v[226:227] op_sel_hi:[1,0]
	v_pk_mul_f32 v[18:19], v[18:19], v[226:227] op_sel_hi:[1,0]
	v_pk_mul_f32 v[20:21], v[20:21], v[226:227] op_sel_hi:[1,0]
	v_pk_mul_f32 v[22:23], v[22:23], v[226:227] op_sel_hi:[1,0]
	v_pk_mul_f32 v[24:25], v[24:25], v[226:227] op_sel_hi:[1,0]
	v_pk_mul_f32 v[26:27], v[26:27], v[226:227] op_sel_hi:[1,0]
	v_pk_mul_f32 v[28:29], v[28:29], v[226:227] op_sel_hi:[1,0]
	v_pk_mul_f32 v[30:31], v[30:31], v[226:227] op_sel_hi:[1,0]
	v_pk_fma_f32 v[0:1], v[136:137], v[0:1], v[152:153]
	v_pk_fma_f32 v[2:3], v[138:139], v[2:3], v[154:155]
	v_pk_fma_f32 v[4:5], v[140:141], v[4:5], v[156:157]
	v_pk_fma_f32 v[6:7], v[142:143], v[6:7], v[158:159]
	v_pk_fma_f32 v[8:9], v[144:145], v[8:9], v[160:161]
	v_pk_fma_f32 v[10:11], v[146:147], v[10:11], v[162:163]
	v_pk_fma_f32 v[12:13], v[148:149], v[12:13], v[164:165]
	v_pk_fma_f32 v[14:15], v[150:151], v[14:15], v[166:167]
	v_pk_fma_f32 v[16:17], v[136:137], v[16:17], v[152:153]
	v_pk_fma_f32 v[18:19], v[138:139], v[18:19], v[154:155]
	v_pk_fma_f32 v[20:21], v[140:141], v[20:21], v[156:157]
	v_pk_fma_f32 v[22:23], v[142:143], v[22:23], v[158:159]
	v_pk_fma_f32 v[24:25], v[144:145], v[24:25], v[160:161]
	v_pk_fma_f32 v[26:27], v[146:147], v[26:27], v[162:163]
	v_pk_fma_f32 v[28:29], v[148:149], v[28:29], v[164:165]
	v_pk_fma_f32 v[30:31], v[150:151], v[30:31], v[166:167]
	v_mov_b32_e32 v228, v212
	v_mov_b32_e32 v229, v214
	v_mov_b32_e32 v168, v224
	v_mov_b32_e32 v169, v226
	v_add_f32_e32 v80, 1.0, v80
	v_add_f32_e32 v81, 1.0, v81
	v_add_f32_e32 v82, 1.0, v82
	v_add_f32_e32 v83, 1.0, v83
	v_add_f32_e32 v84, 1.0, v84
	v_add_f32_e32 v85, 1.0, v85
	v_add_f32_e32 v86, 1.0, v86
	v_add_f32_e32 v87, 1.0, v87
	v_add_f32_e32 v88, 1.0, v88
	v_add_f32_e32 v89, 1.0, v89
	v_add_f32_e32 v90, 1.0, v90
	v_add_f32_e32 v91, 1.0, v91
	v_add_f32_e32 v92, 1.0, v92
	v_add_f32_e32 v93, 1.0, v93
	v_add_f32_e32 v94, 1.0, v94
	v_add_f32_e32 v95, 1.0, v95
	v_pk_fma_f32 v[204:205], v[80:81], v[0:1], v[64:65]
	v_pk_fma_f32 v[206:207], v[82:83], v[2:3], v[66:67]
	v_pk_fma_f32 v[208:209], v[84:85], v[4:5], v[68:69]
	v_pk_fma_f32 v[210:211], v[86:87], v[6:7], v[70:71]
	v_pk_fma_f32 v[212:213], v[88:89], v[8:9], v[72:73]
	v_pk_fma_f32 v[214:215], v[90:91], v[10:11], v[74:75]
	v_pk_fma_f32 v[216:217], v[92:93], v[12:13], v[76:77]
	v_pk_fma_f32 v[218:219], v[94:95], v[14:15], v[78:79]
	v_cvt_pk_bf16_f32 v220, v204, v205
	v_cvt_pk_bf16_f32 v221, v206, v207
	v_cvt_pk_bf16_f32 v222, v208, v209
	v_cvt_pk_bf16_f32 v223, v210, v211
	v_cvt_pk_bf16_f32 v224, v212, v213
	v_cvt_pk_bf16_f32 v225, v214, v215
	v_cvt_pk_bf16_f32 v226, v216, v217
	v_cvt_pk_bf16_f32 v227, v218, v219
	s_mul_i32 s4, s6, 0x880
	s_add_u32 s4, s4, 0xf266000
	s_add_u32 s4, s4, s8
	s_addc_u32 s5, s9, 0
	global_store_dwordx2 v233, v[220:221], s[4:5]
	global_store_dwordx2 v233, v[222:223], s[4:5] offset:512
	global_store_dwordx2 v233, v[224:225], s[4:5] offset:1024
	global_store_dwordx2 v233, v[226:227], s[4:5] offset:1536
	s_mov_b64 s[12:13], exec
	s_mov_b64 exec, 1
	global_store_dwordx2 v129, v[228:229], s[4:5] offset:2048
	s_mov_b64 exec, s[12:13]
	v_pk_fma_f32 v[204:205], v[80:81], v[16:17], v[64:65]
	v_pk_fma_f32 v[206:207], v[82:83], v[18:19], v[66:67]
	v_pk_fma_f32 v[208:209], v[84:85], v[20:21], v[68:69]
	v_pk_fma_f32 v[210:211], v[86:87], v[22:23], v[70:71]
	v_pk_fma_f32 v[212:213], v[88:89], v[24:25], v[72:73]
	v_pk_fma_f32 v[214:215], v[90:91], v[26:27], v[74:75]
	v_pk_fma_f32 v[216:217], v[92:93], v[28:29], v[76:77]
	v_pk_fma_f32 v[218:219], v[94:95], v[30:31], v[78:79]
	v_cvt_pk_bf16_f32 v220, v204, v205
	v_cvt_pk_bf16_f32 v221, v206, v207
	v_cvt_pk_bf16_f32 v222, v208, v209
	v_cvt_pk_bf16_f32 v223, v210, v211
	v_cvt_pk_bf16_f32 v224, v212, v213
	v_cvt_pk_bf16_f32 v225, v214, v215
	v_cvt_pk_bf16_f32 v226, v216, v217
	v_cvt_pk_bf16_f32 v227, v218, v219
	s_mul_i32 s4, s6, 0x880
	s_add_u32 s4, s4, 0xf6a6000
	s_add_u32 s4, s4, s8
	s_addc_u32 s5, s9, 0
	global_store_dwordx2 v233, v[220:221], s[4:5]
	global_store_dwordx2 v233, v[222:223], s[4:5] offset:512
	global_store_dwordx2 v233, v[224:225], s[4:5] offset:1024
	global_store_dwordx2 v233, v[226:227], s[4:5] offset:1536
	s_mov_b64 s[12:13], exec
	s_mov_b64 exec, 1
	global_store_dwordx2 v129, v[168:169], s[4:5] offset:2048
	s_mov_b64 exec, s[12:13]
	s_waitcnt vmcnt(0)
	s_branch .LBB0_1420
